# merge phase: gate GEMMs paired (B halves = same 128 columns of gates 2p and 2p+1), hand-written epilogue sums both gates of a pair in registers: bf16 running-sum scratch written/read once per half til
# speedup vs baseline: 1.0308x; 1.0192x over previous
; DI int half_() { return __builtin_amdgcn_readfirstlane((int)(threadIdx.x >> 8)); }
; __global__ void __launch_bounds__(512, 2) mega(Params p_unused, int ph0, int ph1) {
;   __shared__ __attribute__((aligned(16))) unsigned char lds_all[LDS_BYTES];
;   unsigned char* ldsb = lds_all + half_() * LDS_HALF;
;   cg::grid_group grid = cg::this_grid();
;   for (int ph = ph0; ph < ph1; ++ph) {
;     const __attribute__((address_space(4))) Params* pp = (const __attribute__((address_space(4))) Params*)__builtin_amdgcn_kernarg_segment_ptr();
;     asm volatile("" : "+s"(pp));
;     PREF p = *pp;
;     if (ph1 < 0) grid.sync();
;     if (ph > ph0) grid_barrier(p.bar, (unsigned)(ph - ph0));
;     if (ph == 0) { run_phase<9>(p, 0, ldsb, lds_all); continue; }
;     int l = (ph - 1) / NPH_LAYER; const int j = (ph - 1) % NPH_LAYER;
;     asm volatile("" : "+s"(l));
.LBB0_1:
	s_lshr_b32 s33, s0, 8
	v_readlane_b32 s0, v254, 1
	v_readlane_b32 s1, v254, 2
	s_add_u32 s2, s0, 0x1a8
	s_addc_u32 s3, s1, 0
	v_writelane_b32 v254, s2, 5
	v_lshrrev_b32_e32 v1, 20, v0
	v_lshrrev_b32_e32 v0, 10, v0
	v_writelane_b32 v254, s3, 6
	v_or_b32_e32 v0, v0, v1
	s_movk_i32 s2, 0x3ff
	v_and_or_b32 v0, v0, s2, v168
	v_readlane_b32 s8, v254, 3
	v_cmp_eq_u32_e64 s[2:3], 0, v0
	v_readlane_b32 s9, v254, 4
	s_load_dword s5, s[0:1], 0x1a8
	v_writelane_b32 v254, s2, 7
	s_cmp_lt_i32 s9, 0
	s_cselect_b64 s[0:1], -1, 0
	v_writelane_b32 v254, s3, 8
	v_cmp_eq_u32_e64 s[2:3], 0, v168
	s_waitcnt lgkmcnt(0)
	s_lshr_b32 s45, s5, 3
	s_mul_i32 s33, s33, 0x12400
	v_writelane_b32 v254, s2, 9
	v_cndmask_b32_e64 v0, 0, 1, s[0:1]
	v_cmp_ne_u32_e64 s[0:1], 1, v0
	v_writelane_b32 v254, s3, 10
	v_mbcnt_lo_u32_b32 v0, -1, 0
	v_readlane_b32 s4, v254, 0
	s_and_b32 s2, s4, 15
	s_xor_b32 s3, s2, 15
	s_add_i32 s3, s5, s3
	s_lshr_b32 s3, s3, 4
	s_lshl_b32 s2, s2, 6
	s_lshr_b32 s46, s4, 3
	s_cmpk_lt_u32 s4, 0x200
	v_writelane_b32 v254, s3, 11
	s_cselect_b64 s[6:7], -1, 0
	s_lshl_b32 s3, s4, 4
	s_and_b32 s47, s3, 0x70
	s_lshl_b32 s3, s4, 3
	s_lshl_b32 s48, s5, 3
	v_writelane_b32 v254, s6, 12
	s_cmpk_lt_i32 s4, 0x100
	s_mov_b32 s53, 0
	v_writelane_b32 v254, s7, 13
	s_cselect_b64 s[6:7], -1, 0
	v_writelane_b32 v254, s6, 14
	s_ashr_i32 s49, s48, 31
	s_lshl_b32 s64, s5, 9
	v_writelane_b32 v254, s7, 15
	s_add_i32 s6, s33, 0x12000
	v_writelane_b32 v254, s6, 16
	s_lshl_b32 s6, s4, 9
	v_writelane_b32 v254, s6, 17
	s_lshl_b64 s[6:7], s[48:49], 11
	v_writelane_b32 v254, s6, 18
	s_ashr_i32 s65, s64, 31
	s_lshl_b32 s70, s4, 1
	v_writelane_b32 v254, s7, 19
	v_writelane_b32 v254, s3, 20
	s_addk_i32 s3, 0x4000
	v_writelane_b32 v254, s3, 21
	s_lshl_b32 s3, s4, 8
	v_writelane_b32 v254, s3, 22
	s_lshl_b32 s3, s5, 8
	v_writelane_b32 v254, s3, 23
	s_add_i32 s3, s33, 0x4000
	v_writelane_b32 v254, s3, 24
	s_lshl_b32 s3, s4, 6
	v_writelane_b32 v254, s3, 25
	s_lshl_b64 s[6:7], s[64:65], 4
	v_writelane_b32 v254, s6, 26
	s_lshl_b32 s3, s5, 10
	s_lshl_b32 s71, s5, 1
	v_writelane_b32 v254, s7, 27
	s_lshl_b64 s[6:7], s[64:65], 5
	v_writelane_b32 v254, s6, 28
	s_lshl_b32 s81, s4, 7
	s_lshl_b32 s84, s5, 7
	v_writelane_b32 v254, s7, 29
	s_lshl_b64 s[6:7], s[48:49], 12
	v_writelane_b32 v254, s6, 30
	s_lshl_b32 s85, s5, 6
	s_movk_i32 s66, 0x200
	v_writelane_b32 v254, s7, 31
	v_writelane_b32 v254, s5, 32
	v_writelane_b32 v254, s3, 33
	s_lshl_b64 s[4:5], s[64:65], 2
	v_writelane_b32 v254, s4, 34
	v_and_b32_e32 v169, 0xff, v168
	s_movk_i32 s67, 0x100
	v_writelane_b32 v254, s5, 35
	v_writelane_b32 v254, s0, 36
	s_lshl_b64 s[72:73], s[64:65], 6
	v_mov_b32_e32 v1, 0
	v_writelane_b32 v254, s1, 37
	s_lshl_b32 s0, s2, 2
	v_writelane_b32 v254, s0, 38
	v_writelane_b32 v254, s45, 39
	v_writelane_b32 v254, s46, 40
	v_writelane_b32 v254, s47, 41
	s_mov_b32 s0, s48
	v_writelane_b32 v254, s0, 42
	s_mov_b32 s88, 0x10000
	v_mov_b32_e32 v170, 0x1000
	v_writelane_b32 v254, s1, 43
	s_mov_b32 s0, s64
	s_mov_b64 s[76:77], 0x80
	s_mov_b64 s[78:79], 0x40080
	s_mov_b64 s[42:43], 0x12b0100
	s_mov_b64 s[82:83], 0x100
	s_mov_b64 s[86:87], 0x40100
	s_mov_b64 s[90:91], 0x180
	s_movk_i32 s89, 0x180
	s_movk_i32 s92, 0x210
	s_movk_i32 s93, 0x80
	v_mov_b32_e32 v171, 0x3727c5ac
	s_mov_b32 s61, 0x800000
	s_movk_i32 s80, 0x1000
	s_mov_b64 s[50:51], 0x580100
	s_mov_b64 s[38:39], 0x780100
	s_mov_b64 s[4:5], 0x580180
	s_mov_b64 s[74:75], 0x780180
	s_movk_i32 s60, 0x1540
	s_movk_i32 s96, 0x300
	s_movk_i32 s97, 0x90
	s_mov_b32 s94, 0xff800000
	v_mbcnt_hi_u32_b32 v172, -1, v0
	v_mov_b32_e32 v163, 1.0
	s_mov_b64 s[2:3], 0xaa000
	v_mov_b32_e32 v173, 0x358637bd
	s_movk_i32 s95, 0x400
	s_mov_b64 s[6:7], 0x40180
	s_movk_i32 s58, 0xaa0
	s_movk_i32 s59, 0x600
	s_movk_i32 s54, 0x2a80
	v_mov_b32_e32 v174, 0x3c0881c4
	v_mov_b32_e32 v175, 0xbab64f3b
	v_mov_b32_e32 v176, 0xff800000
	v_mov_b32_e32 v177, 0x7f800000
	v_not_b32_e32 v178, 63
	v_not_b32_e32 v179, 31
	v_mov_b32_e32 v180, 0x7fc00000
	v_mov_b32_e32 v181, 0x37000000
	s_mov_b32 s34, s8
	v_writelane_b32 v254, s0, 44
	s_nop 1
	v_writelane_b32 v254, s1, 45
	s_branch .LBB0_4

; DI void lds_barrier() { asm volatile("s_waitcnt lgkmcnt(0)\n\ts_barrier" ::: "memory"); }
; #define G_BAR __builtin_amdgcn_s_barrier()
;     ...
;   g_stage_rc(t * 16, r0, c0); g_stage_rc(t * 16 + 8192, r1, c1);
;   const int oa0 = r0 * LDA + c0, oa1 = r1 * LDA + c1, ob0 = r0 * LDB + c0, ob1 = r1 * LDB + c1;
;   const int obr = fr * 64 + fq * 16, rdo = obr ^ (((obr >> 9) & 1) << 5);
;   bf16x8 At[4][2], B0[2][2], B1[2][2];
;   constexpr int nt = K / 64;
;   lds_barrier();
;   G_STAGE(G_SB(0, 0), B, ob0, ob1, LDB, 0, KB(0)); G_STAGE(G_SA(0, 0), A, oa0, oa1, LDA, 0, KA(0));
;   G_STAGE(G_SB(0, 1), B, ob0, ob1, LDB, 128, KB(0)); G_STAGE(G_SA(0, 1), A, oa0, oa1, LDA, 128, KA(0));
;   if (wr == 1) G_BAR;
; DI void merge_phase(PREF p, int l, unsigned char* lds_all) {
;     ...
;     for (int n = 0; n < 4; ++n) {
;       f32x4 acc[2][2][4][2]; zero_acc256(acc);
;       gemm256<1024, 1024, 1024>(acc, p.X + (size_t)mt * 256 * 1024, W + O_WM + ((size_t)n * 1024 + dt * 256) * 1024, shm, p);
.LBB0_101:
	s_add_i32 s23, s23, 1
	s_lshl_b64 s[0:1], s[28:29], 11
	s_add_u32 s40, s46, s0
	s_addc_u32 s41, s47, s1
	s_and_b32 s0, s23, 1
	s_lshl_b32 s0, s0, 22
	s_lshr_b32 s1, s23, 1
	s_lshl_b32 s1, s1, 18
	s_add_u32 s0, s0, s1
	s_add_u32 s40, s40, s0
	s_addc_u32 s41, s41, 0
	s_cmp_lg_u32 s23, 4
	s_cbranch_scc0 .LBB0_87
.LBB0_102:
	s_and_b32 s52, s23, 1
	s_lshl_b32 s52, s52, 11
	s_lshr_b32 s0, s23, 1
	s_lshl_b32 s0, s0, 7
	s_add_i32 s52, s52, s0
	s_add_u32 s0, s52, s28
	v_mov_b32_e32 v0, v168
	s_addc_u32 s1, 0, s29
	s_lshl_b64 s[0:1], s[0:1], 11
	v_lshlrev_b32_e32 v143, 4, v0
	v_and_b32_e32 v2, 32, v0
	v_lshrrev_b32_e32 v4, 1, v0
	v_bitop3_b32 v2, v143, v2, 48 bitop3:0x6c
	s_add_u32 s8, s65, s0
	v_ashrrev_i32_e32 v10, 3, v0
	v_bfe_u32 v13, v0, 2, 4
	s_mov_b32 s0, 0x3ffff0
	v_and_b32_e32 v11, 32, v4
	v_lshrrev_b32_e32 v12, 1, v2
	v_add_u32_e32 v144, 0x2000, v143
	v_and_or_b32 v3, v10, s0, v13
	v_or_b32_e32 v2, v12, v11
	v_ashrrev_i32_e32 v15, 7, v144
	v_and_or_b32 v4, v15, s0, v13
	v_lshl_or_b32 v132, v3, 10, v2
	v_lshl_or_b32 v130, v4, 10, v2
	v_ashrrev_i32_e32 v133, 31, v132
	v_add_u32_e32 v146, 0x10000, v143
	s_addc_u32 s9, s68, s1
	v_lshlrev_b64 v[16:17], 1, v[132:133]
	v_readfirstlane_b32 s0, v146
	v_ashrrev_i32_e32 v131, 31, v130
	v_add_u32_e32 v147, 0x12000, v143
	s_waitcnt lgkmcnt(0)
	s_barrier
	v_lshl_add_u64 v[2:3], s[8:9], 0, v[16:17]
	s_mov_b32 m0, s0
	v_lshlrev_b64 v[18:19], 1, v[130:131]
	v_readfirstlane_b32 s0, v147
	global_load_lds_dwordx4 v[2:3], off
	v_lshl_add_u64 v[6:7], s[8:9], 0, v[18:19]
	s_mov_b32 m0, s0
	v_readfirstlane_b32 s0, v143
	global_load_lds_dwordx4 v[6:7], off
	v_lshl_add_u64 v[8:9], s[26:27], 0, v[16:17]
	s_mov_b32 m0, s0
	v_readfirstlane_b32 s0, v144
	global_load_lds_dwordx4 v[8:9], off
	s_mov_b32 m0, s0
	s_add_u32 s0, s8, 0x200000
	v_add_u32_e32 v149, 0x14000, v143
	v_lshl_add_u64 v[4:5], s[26:27], 0, v[18:19]
	s_addc_u32 s1, s9, 0
	v_readfirstlane_b32 s10, v149
	global_load_lds_dwordx4 v[4:5], off
	v_lshl_add_u64 v[20:21], s[0:1], 0, v[16:17]
	s_mov_b32 m0, s10
	v_add_u32_e32 v150, 0x16000, v143
	global_load_lds_dwordx4 v[20:21], off
	v_lshl_add_u64 v[20:21], s[0:1], 0, v[18:19]
	v_readfirstlane_b32 s0, v150
	v_add_u32_e32 v151, 0x4000, v143
	s_mov_b32 m0, s0
	v_readfirstlane_b32 s0, v151
	v_add_u32_e32 v152, 0x6000, v143
	global_load_lds_dwordx4 v[20:21], off
	v_lshl_add_u64 v[16:17], s[30:31], 0, v[16:17]
	s_mov_b32 m0, s0
	v_readfirstlane_b32 s0, v152
	global_load_lds_dwordx4 v[16:17], off
	v_lshl_add_u64 v[16:17], s[30:31], 0, v[18:19]
	s_mov_b32 m0, s0
	v_ashrrev_i32_e32 v14, 8, v0
	global_load_lds_dwordx4 v[16:17], off
	v_cmp_eq_u32_e32 vcc, 1, v14
	s_and_saveexec_b64 s[10:11], vcc
	s_cbranch_execz .LBB0_104
	s_barrier
; #define G_WAIT_V(n) asm volatile("s_waitcnt vmcnt(" #n ")" ::: "memory")
; #define G_BAR __builtin_amdgcn_s_barrier()
;     ...
;   G_WAIT_V(4); G_BAR;
;   G_STAGE(G_SB(1, 0), B, ob0, ob1, LDB, 0, KB(1)); G_STAGE(G_SA(1, 0), A, oa0, oa1, LDA, 0, KA(1)); G_STAGE(G_SB(1, 1), B, ob0, ob1, LDB, 128, KB(1));
;   G_WAIT_V(6); G_BAR;
; DI void zero_acc256(f32x4 (&a)[2][2][4][2]) {
; #pragma unroll
;   for (int i = 0; i < 2; ++i)
; #pragma unroll
;     for (int j = 0; j < 2; ++j)
; #pragma unroll
;       for (int m = 0; m < 4; ++m)
; #pragma unroll
;         for (int n = 0; n < 2; ++n)
; #pragma unroll
;           for (int e = 0; e < 4; ++e) a[i][j][m][n][e] = 0.f;
; }
.LBB0_104:
	s_or_b64 exec, exec, s[10:11]
	v_add_u32_e32 v153, 0x18000, v143
	v_add_u32_e32 v154, 0x1a000, v143
	v_readfirstlane_b32 s0, v153
	v_lshl_add_u64 v[2:3], v[2:3], 0, s[76:77]
	s_mov_b32 m0, s0
	v_readfirstlane_b32 s0, v154
	v_add_u32_e32 v155, 0x8000, v143
	s_waitcnt vmcnt(4)
	s_barrier
	global_load_lds_dwordx4 v[2:3], off
	v_lshl_add_u64 v[2:3], v[6:7], 0, s[76:77]
	s_mov_b32 m0, s0
	v_readfirstlane_b32 s0, v155
	v_add_u32_e32 v156, 0xa000, v143
	global_load_lds_dwordx4 v[2:3], off
	v_lshl_add_u64 v[2:3], v[8:9], 0, s[76:77]
	s_mov_b32 m0, s0
	v_readfirstlane_b32 s0, v156
	global_load_lds_dwordx4 v[2:3], off
	s_mov_b32 m0, s0
	s_add_u32 s0, s8, 0x200080
	v_add_u32_e32 v157, 0x1c000, v143
	v_lshl_add_u64 v[2:3], v[4:5], 0, s[76:77]
	s_addc_u32 s1, s9, 0
	v_readfirstlane_b32 s8, v157
	global_load_lds_dwordx4 v[2:3], off
	v_lshl_add_u64 v[2:3], v[132:133], 1, s[0:1]
	s_mov_b32 m0, s8
	v_add_u32_e32 v159, 0x1e000, v143
	global_load_lds_dwordx4 v[2:3], off
	v_lshl_add_u64 v[2:3], v[130:131], 1, s[0:1]
	v_readfirstlane_b32 s0, v159
	s_mov_b32 m0, s0
	v_lshlrev_b32_e32 v17, 6, v0
	global_load_lds_dwordx4 v[2:3], off
	v_lshlrev_b32_e32 v2, 10, v15
	v_and_b32_e32 v2, 0xffffc000, v2
	v_lshlrev_b32_e32 v4, 10, v13
	v_lshlrev_b32_e32 v5, 10, v10
	v_and_b32_e32 v16, 48, v0
	v_and_b32_e32 v18, 0x3c0, v17
	v_lshlrev_b32_e32 v20, 2, v0
	v_or3_b32 v2, v12, v2, v4
	v_and_b32_e32 v5, 0xffffc000, v5
	v_or_b32_e32 v19, v18, v16
	v_and_b32_e32 v20, 32, v20
	s_mov_b32 s0, 0x14000
	v_add_u32_e32 v2, v2, v11
	v_or3_b32 v4, v12, v5, v4
	v_bitop3_b32 v8, v19, s0, v20 bitop3:0xde
	s_mov_b32 s0, 0x18000
	v_ashrrev_i32_e32 v3, 31, v2
	v_add_u32_e32 v4, v4, v11
	s_waitcnt vmcnt(6)
	v_bitop3_b32 v9, v19, s0, v20 bitop3:0xde
	s_mov_b32 s0, 0x1c000
	v_lshlrev_b64 v[2:3], 1, v[2:3]
	v_ashrrev_i32_e32 v5, 31, v4
	v_bitop3_b32 v16, v18, v20, v16 bitop3:0x36
	v_bitop3_b32 v6, v19, s88, v20 bitop3:0xde
	v_lshlrev_b32_e32 v7, 13, v14
	v_bitop3_b32 v14, v19, s0, v20 bitop3:0xde
	v_and_b32_e32 v17, 0x3000, v17
	v_lshl_add_u64 v[134:135], s[26:27], 0, v[2:3]
	v_lshlrev_b64 v[4:5], 1, v[4:5]
	v_lshl_add_u64 v[138:139], s[40:41], 0, v[2:3]
	v_mov_b32_e32 v2, 0
	v_lshl_add_u64 v[136:137], s[26:27], 0, v[4:5]
	v_lshl_add_u64 v[140:141], s[40:41], 0, v[4:5]
	s_mov_b32 s10, -2
	s_mov_b64 s[8:9], 0
	v_add_u32_e32 v160, v6, v17
	v_add_u32_e32 v142, v16, v7
	v_add_u32_e32 v158, v8, v17
	v_add_u32_e32 v148, v9, v17
	v_add_u32_e32 v145, v14, v17
	v_mov_b32_e32 v3, v2
	v_mov_b32_e32 v4, v2
	v_mov_b32_e32 v5, v2
	v_mov_b32_e32 v6, v2
	v_mov_b32_e32 v7, v2
	v_mov_b32_e32 v8, v2
	v_mov_b32_e32 v9, v2
	v_mov_b32_e32 v10, v2
	v_mov_b32_e32 v11, v2
	v_mov_b32_e32 v12, v2
	v_mov_b32_e32 v13, v2
	v_mov_b32_e32 v14, v2
	v_mov_b32_e32 v15, v2
	v_mov_b32_e32 v16, v2
	v_mov_b32_e32 v17, v2
	v_mov_b32_e32 v18, v2
	v_mov_b32_e32 v19, v2
	v_mov_b32_e32 v20, v2
	v_mov_b32_e32 v21, v2
	v_mov_b32_e32 v22, v2
	v_mov_b32_e32 v23, v2
	v_mov_b32_e32 v24, v2
	v_mov_b32_e32 v25, v2
	v_mov_b32_e32 v26, v2
	v_mov_b32_e32 v27, v2
	v_mov_b32_e32 v28, v2
	v_mov_b32_e32 v29, v2
	v_mov_b32_e32 v30, v2
	v_mov_b32_e32 v31, v2
	v_mov_b32_e32 v32, v2
	v_mov_b32_e32 v33, v2
	v_mov_b32_e32 v34, v2
	v_mov_b32_e32 v35, v2
	v_mov_b32_e32 v36, v2
	v_mov_b32_e32 v37, v2
	v_mov_b32_e32 v38, v2
	v_mov_b32_e32 v39, v2
	v_mov_b32_e32 v40, v2
	v_mov_b32_e32 v41, v2
	v_mov_b32_e32 v42, v2
	v_mov_b32_e32 v43, v2
	v_mov_b32_e32 v44, v2
	v_mov_b32_e32 v45, v2
	v_mov_b32_e32 v46, v2
	v_mov_b32_e32 v47, v2
	v_mov_b32_e32 v48, v2
	v_mov_b32_e32 v49, v2
	v_mov_b32_e32 v50, v2
	v_mov_b32_e32 v51, v2
	v_mov_b32_e32 v52, v2
	v_mov_b32_e32 v53, v2
	v_mov_b32_e32 v54, v2
	v_mov_b32_e32 v55, v2
	v_mov_b32_e32 v56, v2
	v_mov_b32_e32 v57, v2
	v_mov_b32_e32 v58, v2
	v_mov_b32_e32 v59, v2
	v_mov_b32_e32 v60, v2
	v_mov_b32_e32 v61, v2
	v_mov_b32_e32 v62, v2
	v_mov_b32_e32 v63, v2
	v_mov_b32_e32 v64, v2
	v_mov_b32_e32 v65, v2
	v_mov_b32_e32 v66, v2
	v_mov_b32_e32 v67, v2
	v_mov_b32_e32 v68, v2
	v_mov_b32_e32 v69, v2
	v_mov_b32_e32 v70, v2
	v_mov_b32_e32 v71, v2
	v_mov_b32_e32 v72, v2
	v_mov_b32_e32 v73, v2
	v_mov_b32_e32 v74, v2
	v_mov_b32_e32 v75, v2
	v_mov_b32_e32 v76, v2
	v_mov_b32_e32 v77, v2
	v_mov_b32_e32 v78, v2
	v_mov_b32_e32 v79, v2
	v_mov_b32_e32 v80, v2
	v_mov_b32_e32 v81, v2
	v_mov_b32_e32 v82, v2
	v_mov_b32_e32 v83, v2
	v_mov_b32_e32 v84, v2
	v_mov_b32_e32 v85, v2
	v_mov_b32_e32 v86, v2
	v_mov_b32_e32 v87, v2
	v_mov_b32_e32 v88, v2
	v_mov_b32_e32 v89, v2
	v_mov_b32_e32 v90, v2
	v_mov_b32_e32 v91, v2
	v_mov_b32_e32 v92, v2
	v_mov_b32_e32 v93, v2
	v_mov_b32_e32 v94, v2
	v_mov_b32_e32 v95, v2
	v_mov_b32_e32 v96, v2
	v_mov_b32_e32 v97, v2
	v_mov_b32_e32 v98, v2
	v_mov_b32_e32 v99, v2
	v_mov_b32_e32 v100, v2
	v_mov_b32_e32 v101, v2
	v_mov_b32_e32 v102, v2
	v_mov_b32_e32 v103, v2
	v_mov_b32_e32 v104, v2
	v_mov_b32_e32 v105, v2
	v_mov_b32_e32 v106, v2
	v_mov_b32_e32 v107, v2
	v_mov_b32_e32 v108, v2
	v_mov_b32_e32 v109, v2
	v_mov_b32_e32 v110, v2
	v_mov_b32_e32 v111, v2
	v_mov_b32_e32 v112, v2
	v_mov_b32_e32 v113, v2
	v_mov_b32_e32 v114, v2
	v_mov_b32_e32 v115, v2
	v_mov_b32_e32 v116, v2
	v_mov_b32_e32 v117, v2
	v_mov_b32_e32 v118, v2
	v_mov_b32_e32 v119, v2
	v_mov_b32_e32 v120, v2
	v_mov_b32_e32 v121, v2
	v_mov_b32_e32 v122, v2
	v_mov_b32_e32 v123, v2
	v_mov_b32_e32 v124, v2
	v_mov_b32_e32 v125, v2
	v_mov_b32_e32 v126, v2
	v_mov_b32_e32 v127, v2
	v_mov_b32_e32 v128, v2
	v_mov_b32_e32 v129, v2
	s_barrier

; DI float sigm(float x) { return 1.f / (1.f + __expf(-x)); }
; DI u32x4 pack8(const float* f) { u32x4 o; o.x = pack2(f[0], f[1]); o.y = pack2(f[2], f[3]); o.z = pack2(f[4], f[5]); o.w = pack2(f[6], f[7]); return o; }
; DI int tid512() { int t = threadIdx.x; asm volatile("" : "+v"(t)); return t; }
; DI u32x4* merge_scratch(PREF p, int region) { const int t = tid512(); return (u32x4*)p.fbuf + (size_t)blockIdx.x * 40960 + region * 8192 + (t >> 6) * 1024 + (t & 63); }
; DI void gate_reg(PREF p, int l, int n, f32x4 (&acc)[2][2][4][2], int dt) {
;   const u32x4* sbn = merge_scratch(p, n);
;   u32x4* ssum = merge_scratch(p, 4);
;   const int t = tid512(), wid = t >> 6, lane = t & 63, wc = wid & 3, fr = lane & 15;
;   const float* bm = p.b_merge + (size_t)l * 4096 + n * 1024 + dt * 256 + wc * 32 + fr;
;   float bias[2][2];
; #pragma unroll
;   for (int bj = 0; bj < 2; ++bj)
; #pragma unroll
;     for (int nn = 0; nn < 2; ++nn) bias[bj][nn] = bm[bj * 128 + nn * 16];
; #pragma unroll
;   for (int ai = 0; ai < 2; ++ai)
; #pragma unroll
;     for (int bj = 0; bj < 2; ++bj) {
;       __builtin_amdgcn_sched_barrier(0);
;       u32x4 bn[4], pv[4];
; #pragma unroll
;       for (int m = 0; m < 4; ++m) {
;         bn[m] = sbn[((ai * 2 + bj) * 4 + m) * 64];
;         if (n > 0) pv[m] = ssum[((ai * 2 + bj) * 4 + m) * 64];
;       }
; #pragma unroll
;       for (int m = 0; m < 4; ++m) {
;         float b[8]; unpack8(bn[m], b);
;         float v[8];
; #pragma unroll
;         for (int nn = 0; nn < 2; ++nn)
; #pragma unroll
;           for (int j = 0; j < 4; ++j) v[nn * 4 + j] = sigm(acc[ai][bj][m][nn][j] + bias[bj][nn]) * b[nn * 4 + j];
;         if (n > 0) {
;           float o[8]; unpack8(pv[m], o);
; #pragma unroll
;           for (int e = 0; e < 8; ++e) v[e] += o[e];
;         }
;         if (n < 3) ssum[((ai * 2 + bj) * 4 + m) * 64] = pack8(v);
; #pragma unroll
;         for (int nn = 0; nn < 2; ++nn)
; #pragma unroll
;           for (int j = 0; j < 4; ++j) acc[ai][bj][m][nn][j] = v[nn * 4 + j];
;       }
;     }
; }
.LBB0_108:
	s_or_b64 exec, exec, s[8:9]
	s_and_b32 s42, s23, 1
	s_lshr_b32 s43, s23, 1
	s_lshl_b32 s0, s42, 18
	s_lshl_b32 s1, s43, 12
	s_add_u32 s0, s0, s1
	s_add_u32 s8, s63, s0
	s_addc_u32 s9, s64, 0
	s_add_u32 s10, s8, 0x20000
	s_addc_u32 s11, s9, 0
	s_add_u32 s44, s20, s1
	s_addc_u32 s45, s21, 0
	s_lshl_b32 s0, s42, 13
	s_lshl_b32 s1, s43, 9
	s_add_u32 s0, s0, s1
	s_add_u32 s98, s25, s0
	s_addc_u32 s99, s48, 0
	s_add_u32 s0, s98, 0x1000
	s_addc_u32 s1, s99, 0
	v_lshrrev_b32_e32 v155, 6, v168
	v_lshlrev_b32_e32 v155, 14, v155
	v_and_b32_e32 v142, 63, v168
	v_lshl_or_b32 v142, v142, 4, v155
	v_add_u32_e32 v0, 0x2000, v142
	v_lshlrev_b32_e32 v155, 1, v168
	v_and_b32_e32 v155, 0x180, v155
	v_and_b32_e32 v156, 15, v168
	v_lshl_or_b32 v155, v156, 2, v155
	s_cmp_lg_u32 s42, 0
	s_cbranch_scc1 .Lmy_gp_p1
	global_load_dword v143, v155, s[98:99]
	global_load_dword v144, v155, s[98:99] offset:64
	global_load_dword v145, v155, s[0:1]
	global_load_dword v154, v155, s[0:1] offset:64
	global_load_dwordx4 v[182:185], v142, s[8:9] offset:0
	global_load_dwordx4 v[198:201], v142, s[10:11] offset:0
	global_load_dwordx4 v[186:189], v142, s[8:9] offset:1024
	global_load_dwordx4 v[202:205], v142, s[10:11] offset:1024
	global_load_dwordx4 v[190:193], v142, s[8:9] offset:2048
	global_load_dwordx4 v[206:209], v142, s[10:11] offset:2048
	global_load_dwordx4 v[194:197], v142, s[8:9] offset:3072
	global_load_dwordx4 v[210:213], v142, s[10:11] offset:3072
	global_load_dwordx4 v[230:233], v0, s[8:9] offset:0
	global_load_dwordx4 v[246:249], v0, s[10:11] offset:0
	global_load_dwordx4 v[234:237], v0, s[8:9] offset:1024
	global_load_dwordx4 v[250:253], v0, s[10:11] offset:1024
	global_load_dwordx4 v[238:241], v0, s[8:9] offset:2048
	global_load_dwordx4 v[6:9], v0, s[10:11] offset:2048
	global_load_dwordx4 v[242:245], v0, s[8:9] offset:3072
	global_load_dwordx4 v[18:21], v0, s[10:11] offset:3072
	s_waitcnt vmcnt(14)
	v_add_f32_e32 v158, v158, v143
	v_add_f32_e32 v110, v110, v145
	v_mul_f32_e32 v158, 0xbfb8aa3b, v158
	v_mul_f32_e32 v110, 0xbfb8aa3b, v110
	v_exp_f32_e32 v158, v158
	v_exp_f32_e32 v110, v110
	v_add_f32_e32 v159, v159, v143
	v_add_f32_e32 v111, v111, v145
	v_mul_f32_e32 v159, 0xbfb8aa3b, v159
	v_mul_f32_e32 v111, 0xbfb8aa3b, v111
	v_exp_f32_e32 v159, v159
	v_exp_f32_e32 v111, v111
	v_add_f32_e32 v160, v160, v143
	v_add_f32_e32 v112, v112, v145
	v_mul_f32_e32 v160, 0xbfb8aa3b, v160
	v_mul_f32_e32 v112, 0xbfb8aa3b, v112
	v_exp_f32_e32 v160, v160
	v_exp_f32_e32 v112, v112
	v_add_f32_e32 v161, v161, v143
	v_add_f32_e32 v113, v113, v145
	v_mul_f32_e32 v161, 0xbfb8aa3b, v161
	v_mul_f32_e32 v113, 0xbfb8aa3b, v113
	v_exp_f32_e32 v161, v161
	v_exp_f32_e32 v113, v113
	v_add_f32_e32 v150, v150, v144
	v_add_f32_e32 v106, v106, v154
	v_mul_f32_e32 v150, 0xbfb8aa3b, v150
	v_mul_f32_e32 v106, 0xbfb8aa3b, v106
	v_exp_f32_e32 v150, v150
	v_exp_f32_e32 v106, v106
	v_add_f32_e32 v151, v151, v144
	v_add_f32_e32 v107, v107, v154
	v_mul_f32_e32 v151, 0xbfb8aa3b, v151
	v_mul_f32_e32 v107, 0xbfb8aa3b, v107
	v_exp_f32_e32 v151, v151
	v_exp_f32_e32 v107, v107
	v_add_f32_e32 v152, v152, v144
	v_add_f32_e32 v108, v108, v154
	v_mul_f32_e32 v152, 0xbfb8aa3b, v152
	v_mul_f32_e32 v108, 0xbfb8aa3b, v108
	v_exp_f32_e32 v152, v152
	v_exp_f32_e32 v108, v108
	v_add_f32_e32 v153, v153, v144
	v_add_f32_e32 v109, v109, v154
	v_mul_f32_e32 v153, 0xbfb8aa3b, v153
	v_mul_f32_e32 v109, 0xbfb8aa3b, v109
	v_exp_f32_e32 v153, v153
	v_exp_f32_e32 v109, v109
	v_pk_add_f32 v[158:159], v[158:159], 1.0 op_sel_hi:[1,0]
	v_pk_add_f32 v[110:111], v[110:111], 1.0 op_sel_hi:[1,0]
	v_lshlrev_b32_e32 v156, 16, v182
	v_and_b32_e32 v157, 0xffff0000, v182
	v_rcp_f32_e32 v158, v158
	v_rcp_f32_e32 v159, v159
	v_lshlrev_b32_e32 v164, 16, v198
	v_and_b32_e32 v165, 0xffff0000, v198
	v_rcp_f32_e32 v110, v110
	v_rcp_f32_e32 v111, v111
	v_pk_mul_f32 v[158:159], v[158:159], v[156:157]
	s_nop 0
	v_pk_fma_f32 v[158:159], v[110:111], v[164:165], v[158:159]
	v_pk_add_f32 v[160:161], v[160:161], 1.0 op_sel_hi:[1,0]
	v_pk_add_f32 v[112:113], v[112:113], 1.0 op_sel_hi:[1,0]
	v_lshlrev_b32_e32 v156, 16, v183
	v_and_b32_e32 v157, 0xffff0000, v183
	v_rcp_f32_e32 v160, v160
	v_rcp_f32_e32 v161, v161
	v_lshlrev_b32_e32 v164, 16, v199
	v_and_b32_e32 v165, 0xffff0000, v199
	v_rcp_f32_e32 v112, v112
	v_rcp_f32_e32 v113, v113
	v_pk_mul_f32 v[160:161], v[160:161], v[156:157]
	s_nop 0
	v_pk_fma_f32 v[160:161], v[112:113], v[164:165], v[160:161]
	v_pk_add_f32 v[150:151], v[150:151], 1.0 op_sel_hi:[1,0]
	v_pk_add_f32 v[106:107], v[106:107], 1.0 op_sel_hi:[1,0]
	v_lshlrev_b32_e32 v156, 16, v184
	v_and_b32_e32 v157, 0xffff0000, v184
	v_rcp_f32_e32 v150, v150
	v_rcp_f32_e32 v151, v151
	v_lshlrev_b32_e32 v164, 16, v200
	v_and_b32_e32 v165, 0xffff0000, v200
	v_rcp_f32_e32 v106, v106
	v_rcp_f32_e32 v107, v107
	v_pk_mul_f32 v[150:151], v[150:151], v[156:157]
	s_nop 0
	v_pk_fma_f32 v[150:151], v[106:107], v[164:165], v[150:151]
	v_pk_add_f32 v[152:153], v[152:153], 1.0 op_sel_hi:[1,0]
	v_pk_add_f32 v[108:109], v[108:109], 1.0 op_sel_hi:[1,0]
	v_lshlrev_b32_e32 v156, 16, v185
	v_and_b32_e32 v157, 0xffff0000, v185
	v_rcp_f32_e32 v152, v152
	v_rcp_f32_e32 v153, v153
	v_lshlrev_b32_e32 v164, 16, v201
	v_and_b32_e32 v165, 0xffff0000, v201
	v_rcp_f32_e32 v108, v108
	v_rcp_f32_e32 v109, v109
	v_pk_mul_f32 v[152:153], v[152:153], v[156:157]
	s_nop 0
	v_pk_fma_f32 v[152:153], v[108:109], v[164:165], v[152:153]
	v_cvt_pk_bf16_f32 v182, v158, v159
	v_cvt_pk_bf16_f32 v183, v160, v161
	v_cvt_pk_bf16_f32 v184, v150, v151
	v_cvt_pk_bf16_f32 v185, v152, v153
	global_store_dwordx4 v142, v[182:185], s[44:45] offset:0
	s_waitcnt vmcnt(13)
; DI float sigm(float x) { return 1.f / (1.f + __expf(-x)); }
; DI u32x4 pack8(const float* f) { u32x4 o; o.x = pack2(f[0], f[1]); o.y = pack2(f[2], f[3]); o.z = pack2(f[4], f[5]); o.w = pack2(f[6], f[7]); return o; }
; DI int tid512() { int t = threadIdx.x; asm volatile("" : "+v"(t)); return t; }
; DI u32x4* merge_scratch(PREF p, int region) { const int t = tid512(); return (u32x4*)p.fbuf + (size_t)blockIdx.x * 40960 + region * 8192 + (t >> 6) * 1024 + (t & 63); }
; DI void gate_reg(PREF p, int l, int n, f32x4 (&acc)[2][2][4][2], int dt) {
;   const u32x4* sbn = merge_scratch(p, n);
;   u32x4* ssum = merge_scratch(p, 4);
;   const int t = tid512(), wid = t >> 6, lane = t & 63, wc = wid & 3, fr = lane & 15;
;   const float* bm = p.b_merge + (size_t)l * 4096 + n * 1024 + dt * 256 + wc * 32 + fr;
;   float bias[2][2];
; #pragma unroll
;   for (int bj = 0; bj < 2; ++bj)
; #pragma unroll
;     for (int nn = 0; nn < 2; ++nn) bias[bj][nn] = bm[bj * 128 + nn * 16];
; #pragma unroll
;   for (int ai = 0; ai < 2; ++ai)
; #pragma unroll
;     for (int bj = 0; bj < 2; ++bj) {
;       __builtin_amdgcn_sched_barrier(0);
;       u32x4 bn[4], pv[4];
; #pragma unroll
;       for (int m = 0; m < 4; ++m) {
;         bn[m] = sbn[((ai * 2 + bj) * 4 + m) * 64];
;         if (n > 0) pv[m] = ssum[((ai * 2 + bj) * 4 + m) * 64];
;       }
; #pragma unroll
;       for (int m = 0; m < 4; ++m) {
;         float b[8]; unpack8(bn[m], b);
;         float v[8];
; #pragma unroll
;         for (int nn = 0; nn < 2; ++nn)
; #pragma unroll
;           for (int j = 0; j < 4; ++j) v[nn * 4 + j] = sigm(acc[ai][bj][m][nn][j] + bias[bj][nn]) * b[nn * 4 + j];
;         if (n > 0) {
;           float o[8]; unpack8(pv[m], o);
; #pragma unroll
;           for (int e = 0; e < 8; ++e) v[e] += o[e];
;         }
;         if (n < 3) ssum[((ai * 2 + bj) * 4 + m) * 64] = pack8(v);
; #pragma unroll
;         for (int nn = 0; nn < 2; ++nn)
; #pragma unroll
;           for (int j = 0; j < 4; ++j) acc[ai][bj][m][nn][j] = v[nn * 4 + j];
;       }
;     }
; }
	v_add_f32_e32 v146, v146, v143
	v_add_f32_e32 v102, v102, v145
	v_mul_f32_e32 v146, 0xbfb8aa3b, v146
	v_mul_f32_e32 v102, 0xbfb8aa3b, v102
	v_exp_f32_e32 v146, v146
	v_exp_f32_e32 v102, v102
	v_add_f32_e32 v147, v147, v143
	v_add_f32_e32 v103, v103, v145
	v_mul_f32_e32 v147, 0xbfb8aa3b, v147
	v_mul_f32_e32 v103, 0xbfb8aa3b, v103
	v_exp_f32_e32 v147, v147
	v_exp_f32_e32 v103, v103
	v_add_f32_e32 v148, v148, v143
	v_add_f32_e32 v104, v104, v145
	v_mul_f32_e32 v148, 0xbfb8aa3b, v148
	v_mul_f32_e32 v104, 0xbfb8aa3b, v104
	v_exp_f32_e32 v148, v148
	v_exp_f32_e32 v104, v104
	v_add_f32_e32 v149, v149, v143
	v_add_f32_e32 v105, v105, v145
	v_mul_f32_e32 v149, 0xbfb8aa3b, v149
	v_mul_f32_e32 v105, 0xbfb8aa3b, v105
	v_exp_f32_e32 v149, v149
	v_exp_f32_e32 v105, v105
	v_add_f32_e32 v138, v138, v144
	v_add_f32_e32 v98, v98, v154
	v_mul_f32_e32 v138, 0xbfb8aa3b, v138
	v_mul_f32_e32 v98, 0xbfb8aa3b, v98
	v_exp_f32_e32 v138, v138
	v_exp_f32_e32 v98, v98
	v_add_f32_e32 v139, v139, v144
	v_add_f32_e32 v99, v99, v154
	v_mul_f32_e32 v139, 0xbfb8aa3b, v139
	v_mul_f32_e32 v99, 0xbfb8aa3b, v99
	v_exp_f32_e32 v139, v139
	v_exp_f32_e32 v99, v99
	v_add_f32_e32 v140, v140, v144
	v_add_f32_e32 v100, v100, v154
	v_mul_f32_e32 v140, 0xbfb8aa3b, v140
	v_mul_f32_e32 v100, 0xbfb8aa3b, v100
	v_exp_f32_e32 v140, v140
	v_exp_f32_e32 v100, v100
	v_add_f32_e32 v141, v141, v144
	v_add_f32_e32 v101, v101, v154
	v_mul_f32_e32 v141, 0xbfb8aa3b, v141
	v_mul_f32_e32 v101, 0xbfb8aa3b, v101
	v_exp_f32_e32 v141, v141
	v_exp_f32_e32 v101, v101
	v_pk_add_f32 v[146:147], v[146:147], 1.0 op_sel_hi:[1,0]
	v_pk_add_f32 v[102:103], v[102:103], 1.0 op_sel_hi:[1,0]
	v_lshlrev_b32_e32 v156, 16, v186
	v_and_b32_e32 v157, 0xffff0000, v186
	v_rcp_f32_e32 v146, v146
	v_rcp_f32_e32 v147, v147
	v_lshlrev_b32_e32 v164, 16, v202
	v_and_b32_e32 v165, 0xffff0000, v202
	v_rcp_f32_e32 v102, v102
	v_rcp_f32_e32 v103, v103
	v_pk_mul_f32 v[146:147], v[146:147], v[156:157]
	s_nop 0
	v_pk_fma_f32 v[146:147], v[102:103], v[164:165], v[146:147]
	v_pk_add_f32 v[148:149], v[148:149], 1.0 op_sel_hi:[1,0]
	v_pk_add_f32 v[104:105], v[104:105], 1.0 op_sel_hi:[1,0]
	v_lshlrev_b32_e32 v156, 16, v187
	v_and_b32_e32 v157, 0xffff0000, v187
	v_rcp_f32_e32 v148, v148
	v_rcp_f32_e32 v149, v149
	v_lshlrev_b32_e32 v164, 16, v203
	v_and_b32_e32 v165, 0xffff0000, v203
	v_rcp_f32_e32 v104, v104
	v_rcp_f32_e32 v105, v105
	v_pk_mul_f32 v[148:149], v[148:149], v[156:157]
	s_nop 0
	v_pk_fma_f32 v[148:149], v[104:105], v[164:165], v[148:149]
	v_pk_add_f32 v[138:139], v[138:139], 1.0 op_sel_hi:[1,0]
	v_pk_add_f32 v[98:99], v[98:99], 1.0 op_sel_hi:[1,0]
	v_lshlrev_b32_e32 v156, 16, v188
	v_and_b32_e32 v157, 0xffff0000, v188
	v_rcp_f32_e32 v138, v138
	v_rcp_f32_e32 v139, v139
	v_lshlrev_b32_e32 v164, 16, v204
	v_and_b32_e32 v165, 0xffff0000, v204
	v_rcp_f32_e32 v98, v98
	v_rcp_f32_e32 v99, v99
	v_pk_mul_f32 v[138:139], v[138:139], v[156:157]
	s_nop 0
	v_pk_fma_f32 v[138:139], v[98:99], v[164:165], v[138:139]
	v_pk_add_f32 v[140:141], v[140:141], 1.0 op_sel_hi:[1,0]
	v_pk_add_f32 v[100:101], v[100:101], 1.0 op_sel_hi:[1,0]
	v_lshlrev_b32_e32 v156, 16, v189
	v_and_b32_e32 v157, 0xffff0000, v189
	v_rcp_f32_e32 v140, v140
	v_rcp_f32_e32 v141, v141
	v_lshlrev_b32_e32 v164, 16, v205
	v_and_b32_e32 v165, 0xffff0000, v205
	v_rcp_f32_e32 v100, v100
	v_rcp_f32_e32 v101, v101
	v_pk_mul_f32 v[140:141], v[140:141], v[156:157]
	s_nop 0
	v_pk_fma_f32 v[140:141], v[100:101], v[164:165], v[140:141]
	v_cvt_pk_bf16_f32 v186, v146, v147
	v_cvt_pk_bf16_f32 v187, v148, v149
	v_cvt_pk_bf16_f32 v188, v138, v139
	v_cvt_pk_bf16_f32 v189, v140, v141
	global_store_dwordx4 v142, v[186:189], s[44:45] offset:1024
	s_waitcnt vmcnt(12)
	v_add_f32_e32 v134, v134, v143
	v_add_f32_e32 v94, v94, v145
	v_mul_f32_e32 v134, 0xbfb8aa3b, v134
	v_mul_f32_e32 v94, 0xbfb8aa3b, v94
	v_exp_f32_e32 v134, v134
	v_exp_f32_e32 v94, v94
	v_add_f32_e32 v135, v135, v143
	v_add_f32_e32 v95, v95, v145
	v_mul_f32_e32 v135, 0xbfb8aa3b, v135
	v_mul_f32_e32 v95, 0xbfb8aa3b, v95
	v_exp_f32_e32 v135, v135
	v_exp_f32_e32 v95, v95
	v_add_f32_e32 v136, v136, v143
	v_add_f32_e32 v96, v96, v145
	v_mul_f32_e32 v136, 0xbfb8aa3b, v136
	v_mul_f32_e32 v96, 0xbfb8aa3b, v96
	v_exp_f32_e32 v136, v136
	v_exp_f32_e32 v96, v96
	v_add_f32_e32 v137, v137, v143
	v_add_f32_e32 v97, v97, v145
	v_mul_f32_e32 v137, 0xbfb8aa3b, v137
	v_mul_f32_e32 v97, 0xbfb8aa3b, v97
	v_exp_f32_e32 v137, v137
	v_exp_f32_e32 v97, v97
	v_add_f32_e32 v126, v126, v144
	v_add_f32_e32 v90, v90, v154
	v_mul_f32_e32 v126, 0xbfb8aa3b, v126
	v_mul_f32_e32 v90, 0xbfb8aa3b, v90
	v_exp_f32_e32 v126, v126
	v_exp_f32_e32 v90, v90
	v_add_f32_e32 v127, v127, v144
	v_add_f32_e32 v91, v91, v154
	v_mul_f32_e32 v127, 0xbfb8aa3b, v127
	v_mul_f32_e32 v91, 0xbfb8aa3b, v91
	v_exp_f32_e32 v127, v127
	v_exp_f32_e32 v91, v91
	v_add_f32_e32 v128, v128, v144
	v_add_f32_e32 v92, v92, v154
	v_mul_f32_e32 v128, 0xbfb8aa3b, v128
	v_mul_f32_e32 v92, 0xbfb8aa3b, v92
	v_exp_f32_e32 v128, v128
	v_exp_f32_e32 v92, v92
	v_add_f32_e32 v129, v129, v144
	v_add_f32_e32 v93, v93, v154
	v_mul_f32_e32 v129, 0xbfb8aa3b, v129
	v_mul_f32_e32 v93, 0xbfb8aa3b, v93
	v_exp_f32_e32 v129, v129
	v_exp_f32_e32 v93, v93
	v_pk_add_f32 v[134:135], v[134:135], 1.0 op_sel_hi:[1,0]
	v_pk_add_f32 v[94:95], v[94:95], 1.0 op_sel_hi:[1,0]
	v_lshlrev_b32_e32 v156, 16, v190
	v_and_b32_e32 v157, 0xffff0000, v190
	v_rcp_f32_e32 v134, v134
	v_rcp_f32_e32 v135, v135
	v_lshlrev_b32_e32 v164, 16, v206
	v_and_b32_e32 v165, 0xffff0000, v206
	v_rcp_f32_e32 v94, v94
	v_rcp_f32_e32 v95, v95
	v_pk_mul_f32 v[134:135], v[134:135], v[156:157]
	s_nop 0
	v_pk_fma_f32 v[134:135], v[94:95], v[164:165], v[134:135]
; DI float sigm(float x) { return 1.f / (1.f + __expf(-x)); }
; DI u32x4 pack8(const float* f) { u32x4 o; o.x = pack2(f[0], f[1]); o.y = pack2(f[2], f[3]); o.z = pack2(f[4], f[5]); o.w = pack2(f[6], f[7]); return o; }
; DI int tid512() { int t = threadIdx.x; asm volatile("" : "+v"(t)); return t; }
; DI u32x4* merge_scratch(PREF p, int region) { const int t = tid512(); return (u32x4*)p.fbuf + (size_t)blockIdx.x * 40960 + region * 8192 + (t >> 6) * 1024 + (t & 63); }
; DI void gate_reg(PREF p, int l, int n, f32x4 (&acc)[2][2][4][2], int dt) {
;   const u32x4* sbn = merge_scratch(p, n);
;   u32x4* ssum = merge_scratch(p, 4);
;   const int t = tid512(), wid = t >> 6, lane = t & 63, wc = wid & 3, fr = lane & 15;
;   const float* bm = p.b_merge + (size_t)l * 4096 + n * 1024 + dt * 256 + wc * 32 + fr;
;   float bias[2][2];
; #pragma unroll
;   for (int bj = 0; bj < 2; ++bj)
; #pragma unroll
;     for (int nn = 0; nn < 2; ++nn) bias[bj][nn] = bm[bj * 128 + nn * 16];
; #pragma unroll
;   for (int ai = 0; ai < 2; ++ai)
; #pragma unroll
;     for (int bj = 0; bj < 2; ++bj) {
;       __builtin_amdgcn_sched_barrier(0);
;       u32x4 bn[4], pv[4];
; #pragma unroll
;       for (int m = 0; m < 4; ++m) {
;         bn[m] = sbn[((ai * 2 + bj) * 4 + m) * 64];
;         if (n > 0) pv[m] = ssum[((ai * 2 + bj) * 4 + m) * 64];
;       }
; #pragma unroll
;       for (int m = 0; m < 4; ++m) {
;         float b[8]; unpack8(bn[m], b);
;         float v[8];
; #pragma unroll
;         for (int nn = 0; nn < 2; ++nn)
; #pragma unroll
;           for (int j = 0; j < 4; ++j) v[nn * 4 + j] = sigm(acc[ai][bj][m][nn][j] + bias[bj][nn]) * b[nn * 4 + j];
;         if (n > 0) {
;           float o[8]; unpack8(pv[m], o);
; #pragma unroll
;           for (int e = 0; e < 8; ++e) v[e] += o[e];
;         }
;         if (n < 3) ssum[((ai * 2 + bj) * 4 + m) * 64] = pack8(v);
; #pragma unroll
;         for (int nn = 0; nn < 2; ++nn)
; #pragma unroll
;           for (int j = 0; j < 4; ++j) acc[ai][bj][m][nn][j] = v[nn * 4 + j];
;       }
;     }
; }
	v_pk_add_f32 v[136:137], v[136:137], 1.0 op_sel_hi:[1,0]
	v_pk_add_f32 v[96:97], v[96:97], 1.0 op_sel_hi:[1,0]
	v_lshlrev_b32_e32 v156, 16, v191
	v_and_b32_e32 v157, 0xffff0000, v191
	v_rcp_f32_e32 v136, v136
	v_rcp_f32_e32 v137, v137
	v_lshlrev_b32_e32 v164, 16, v207
	v_and_b32_e32 v165, 0xffff0000, v207
	v_rcp_f32_e32 v96, v96
	v_rcp_f32_e32 v97, v97
	v_pk_mul_f32 v[136:137], v[136:137], v[156:157]
	s_nop 0
	v_pk_fma_f32 v[136:137], v[96:97], v[164:165], v[136:137]
	v_pk_add_f32 v[126:127], v[126:127], 1.0 op_sel_hi:[1,0]
	v_pk_add_f32 v[90:91], v[90:91], 1.0 op_sel_hi:[1,0]
	v_lshlrev_b32_e32 v156, 16, v192
	v_and_b32_e32 v157, 0xffff0000, v192
	v_rcp_f32_e32 v126, v126
	v_rcp_f32_e32 v127, v127
	v_lshlrev_b32_e32 v164, 16, v208
	v_and_b32_e32 v165, 0xffff0000, v208
	v_rcp_f32_e32 v90, v90
	v_rcp_f32_e32 v91, v91
	v_pk_mul_f32 v[126:127], v[126:127], v[156:157]
	s_nop 0
	v_pk_fma_f32 v[126:127], v[90:91], v[164:165], v[126:127]
	v_pk_add_f32 v[128:129], v[128:129], 1.0 op_sel_hi:[1,0]
	v_pk_add_f32 v[92:93], v[92:93], 1.0 op_sel_hi:[1,0]
	v_lshlrev_b32_e32 v156, 16, v193
	v_and_b32_e32 v157, 0xffff0000, v193
	v_rcp_f32_e32 v128, v128
	v_rcp_f32_e32 v129, v129
	v_lshlrev_b32_e32 v164, 16, v209
	v_and_b32_e32 v165, 0xffff0000, v209
	v_rcp_f32_e32 v92, v92
	v_rcp_f32_e32 v93, v93
	v_pk_mul_f32 v[128:129], v[128:129], v[156:157]
	s_nop 0
	v_pk_fma_f32 v[128:129], v[92:93], v[164:165], v[128:129]
	v_cvt_pk_bf16_f32 v190, v134, v135
	v_cvt_pk_bf16_f32 v191, v136, v137
	v_cvt_pk_bf16_f32 v192, v126, v127
	v_cvt_pk_bf16_f32 v193, v128, v129
	global_store_dwordx4 v142, v[190:193], s[44:45] offset:2048
	s_waitcnt vmcnt(11)
	v_add_f32_e32 v122, v122, v143
	v_add_f32_e32 v86, v86, v145
	v_mul_f32_e32 v122, 0xbfb8aa3b, v122
	v_mul_f32_e32 v86, 0xbfb8aa3b, v86
	v_exp_f32_e32 v122, v122
	v_exp_f32_e32 v86, v86
	v_add_f32_e32 v123, v123, v143
	v_add_f32_e32 v87, v87, v145
	v_mul_f32_e32 v123, 0xbfb8aa3b, v123
	v_mul_f32_e32 v87, 0xbfb8aa3b, v87
	v_exp_f32_e32 v123, v123
	v_exp_f32_e32 v87, v87
	v_add_f32_e32 v124, v124, v143
	v_add_f32_e32 v88, v88, v145
	v_mul_f32_e32 v124, 0xbfb8aa3b, v124
	v_mul_f32_e32 v88, 0xbfb8aa3b, v88
	v_exp_f32_e32 v124, v124
	v_exp_f32_e32 v88, v88
	v_add_f32_e32 v125, v125, v143
	v_add_f32_e32 v89, v89, v145
	v_mul_f32_e32 v125, 0xbfb8aa3b, v125
	v_mul_f32_e32 v89, 0xbfb8aa3b, v89
	v_exp_f32_e32 v125, v125
	v_exp_f32_e32 v89, v89
	v_add_f32_e32 v114, v114, v144
	v_add_f32_e32 v82, v82, v154
	v_mul_f32_e32 v114, 0xbfb8aa3b, v114
	v_mul_f32_e32 v82, 0xbfb8aa3b, v82
	v_exp_f32_e32 v114, v114
	v_exp_f32_e32 v82, v82
	v_add_f32_e32 v115, v115, v144
	v_add_f32_e32 v83, v83, v154
	v_mul_f32_e32 v115, 0xbfb8aa3b, v115
	v_mul_f32_e32 v83, 0xbfb8aa3b, v83
	v_exp_f32_e32 v115, v115
	v_exp_f32_e32 v83, v83
	v_add_f32_e32 v116, v116, v144
	v_add_f32_e32 v84, v84, v154
	v_mul_f32_e32 v116, 0xbfb8aa3b, v116
	v_mul_f32_e32 v84, 0xbfb8aa3b, v84
	v_exp_f32_e32 v116, v116
	v_exp_f32_e32 v84, v84
	v_add_f32_e32 v117, v117, v144
	v_add_f32_e32 v85, v85, v154
	v_mul_f32_e32 v117, 0xbfb8aa3b, v117
	v_mul_f32_e32 v85, 0xbfb8aa3b, v85
	v_exp_f32_e32 v117, v117
	v_exp_f32_e32 v85, v85
	v_pk_add_f32 v[122:123], v[122:123], 1.0 op_sel_hi:[1,0]
	v_pk_add_f32 v[86:87], v[86:87], 1.0 op_sel_hi:[1,0]
	v_lshlrev_b32_e32 v156, 16, v194
	v_and_b32_e32 v157, 0xffff0000, v194
	v_rcp_f32_e32 v122, v122
	v_rcp_f32_e32 v123, v123
	v_lshlrev_b32_e32 v164, 16, v210
	v_and_b32_e32 v165, 0xffff0000, v210
	v_rcp_f32_e32 v86, v86
	v_rcp_f32_e32 v87, v87
	v_pk_mul_f32 v[122:123], v[122:123], v[156:157]
	s_nop 0
	v_pk_fma_f32 v[122:123], v[86:87], v[164:165], v[122:123]
	v_pk_add_f32 v[124:125], v[124:125], 1.0 op_sel_hi:[1,0]
	v_pk_add_f32 v[88:89], v[88:89], 1.0 op_sel_hi:[1,0]
	v_lshlrev_b32_e32 v156, 16, v195
	v_and_b32_e32 v157, 0xffff0000, v195
	v_rcp_f32_e32 v124, v124
	v_rcp_f32_e32 v125, v125
	v_lshlrev_b32_e32 v164, 16, v211
	v_and_b32_e32 v165, 0xffff0000, v211
	v_rcp_f32_e32 v88, v88
	v_rcp_f32_e32 v89, v89
	v_pk_mul_f32 v[124:125], v[124:125], v[156:157]
	s_nop 0
	v_pk_fma_f32 v[124:125], v[88:89], v[164:165], v[124:125]
	v_pk_add_f32 v[114:115], v[114:115], 1.0 op_sel_hi:[1,0]
	v_pk_add_f32 v[82:83], v[82:83], 1.0 op_sel_hi:[1,0]
	v_lshlrev_b32_e32 v156, 16, v196
	v_and_b32_e32 v157, 0xffff0000, v196
	v_rcp_f32_e32 v114, v114
	v_rcp_f32_e32 v115, v115
	v_lshlrev_b32_e32 v164, 16, v212
	v_and_b32_e32 v165, 0xffff0000, v212
	v_rcp_f32_e32 v82, v82
	v_rcp_f32_e32 v83, v83
	v_pk_mul_f32 v[114:115], v[114:115], v[156:157]
	s_nop 0
	v_pk_fma_f32 v[114:115], v[82:83], v[164:165], v[114:115]
	v_pk_add_f32 v[116:117], v[116:117], 1.0 op_sel_hi:[1,0]
	v_pk_add_f32 v[84:85], v[84:85], 1.0 op_sel_hi:[1,0]
	v_lshlrev_b32_e32 v156, 16, v197
	v_and_b32_e32 v157, 0xffff0000, v197
	v_rcp_f32_e32 v116, v116
	v_rcp_f32_e32 v117, v117
	v_lshlrev_b32_e32 v164, 16, v213
	v_and_b32_e32 v165, 0xffff0000, v213
	v_rcp_f32_e32 v84, v84
	v_rcp_f32_e32 v85, v85
	v_pk_mul_f32 v[116:117], v[116:117], v[156:157]
	s_nop 0
	v_pk_fma_f32 v[116:117], v[84:85], v[164:165], v[116:117]
	v_cvt_pk_bf16_f32 v194, v122, v123
	v_cvt_pk_bf16_f32 v195, v124, v125
	v_cvt_pk_bf16_f32 v196, v114, v115
	v_cvt_pk_bf16_f32 v197, v116, v117
	global_store_dwordx4 v142, v[194:197], s[44:45] offset:3072
	s_waitcnt vmcnt(10)
; DI float sigm(float x) { return 1.f / (1.f + __expf(-x)); }
; DI u32x4 pack8(const float* f) { u32x4 o; o.x = pack2(f[0], f[1]); o.y = pack2(f[2], f[3]); o.z = pack2(f[4], f[5]); o.w = pack2(f[6], f[7]); return o; }
; DI int tid512() { int t = threadIdx.x; asm volatile("" : "+v"(t)); return t; }
; DI u32x4* merge_scratch(PREF p, int region) { const int t = tid512(); return (u32x4*)p.fbuf + (size_t)blockIdx.x * 40960 + region * 8192 + (t >> 6) * 1024 + (t & 63); }
; DI void gate_reg(PREF p, int l, int n, f32x4 (&acc)[2][2][4][2], int dt) {
;   const u32x4* sbn = merge_scratch(p, n);
;   u32x4* ssum = merge_scratch(p, 4);
;   const int t = tid512(), wid = t >> 6, lane = t & 63, wc = wid & 3, fr = lane & 15;
;   const float* bm = p.b_merge + (size_t)l * 4096 + n * 1024 + dt * 256 + wc * 32 + fr;
;   float bias[2][2];
; #pragma unroll
;   for (int bj = 0; bj < 2; ++bj)
; #pragma unroll
;     for (int nn = 0; nn < 2; ++nn) bias[bj][nn] = bm[bj * 128 + nn * 16];
; #pragma unroll
;   for (int ai = 0; ai < 2; ++ai)
; #pragma unroll
;     for (int bj = 0; bj < 2; ++bj) {
;       __builtin_amdgcn_sched_barrier(0);
;       u32x4 bn[4], pv[4];
; #pragma unroll
;       for (int m = 0; m < 4; ++m) {
;         bn[m] = sbn[((ai * 2 + bj) * 4 + m) * 64];
;         if (n > 0) pv[m] = ssum[((ai * 2 + bj) * 4 + m) * 64];
;       }
; #pragma unroll
;       for (int m = 0; m < 4; ++m) {
;         float b[8]; unpack8(bn[m], b);
;         float v[8];
; #pragma unroll
;         for (int nn = 0; nn < 2; ++nn)
; #pragma unroll
;           for (int j = 0; j < 4; ++j) v[nn * 4 + j] = sigm(acc[ai][bj][m][nn][j] + bias[bj][nn]) * b[nn * 4 + j];
;         if (n > 0) {
;           float o[8]; unpack8(pv[m], o);
; #pragma unroll
;           for (int e = 0; e < 8; ++e) v[e] += o[e];
;         }
;         if (n < 3) ssum[((ai * 2 + bj) * 4 + m) * 64] = pack8(v);
; #pragma unroll
;         for (int nn = 0; nn < 2; ++nn)
; #pragma unroll
;           for (int j = 0; j < 4; ++j) acc[ai][bj][m][nn][j] = v[nn * 4 + j];
;       }
;     }
; }
	v_add_f32_e32 v78, v78, v143
	v_add_f32_e32 v46, v46, v145
	v_mul_f32_e32 v78, 0xbfb8aa3b, v78
	v_mul_f32_e32 v46, 0xbfb8aa3b, v46
	v_exp_f32_e32 v78, v78
	v_exp_f32_e32 v46, v46
	v_add_f32_e32 v79, v79, v143
	v_add_f32_e32 v47, v47, v145
	v_mul_f32_e32 v79, 0xbfb8aa3b, v79
	v_mul_f32_e32 v47, 0xbfb8aa3b, v47
	v_exp_f32_e32 v79, v79
	v_exp_f32_e32 v47, v47
	v_add_f32_e32 v80, v80, v143
	v_add_f32_e32 v48, v48, v145
	v_mul_f32_e32 v80, 0xbfb8aa3b, v80
	v_mul_f32_e32 v48, 0xbfb8aa3b, v48
	v_exp_f32_e32 v80, v80
	v_exp_f32_e32 v48, v48
	v_add_f32_e32 v81, v81, v143
	v_add_f32_e32 v49, v49, v145
	v_mul_f32_e32 v81, 0xbfb8aa3b, v81
	v_mul_f32_e32 v49, 0xbfb8aa3b, v49
	v_exp_f32_e32 v81, v81
	v_exp_f32_e32 v49, v49
	v_add_f32_e32 v74, v74, v144
	v_add_f32_e32 v38, v38, v154
	v_mul_f32_e32 v74, 0xbfb8aa3b, v74
	v_mul_f32_e32 v38, 0xbfb8aa3b, v38
	v_exp_f32_e32 v74, v74
	v_exp_f32_e32 v38, v38
	v_add_f32_e32 v75, v75, v144
	v_add_f32_e32 v39, v39, v154
	v_mul_f32_e32 v75, 0xbfb8aa3b, v75
	v_mul_f32_e32 v39, 0xbfb8aa3b, v39
	v_exp_f32_e32 v75, v75
	v_exp_f32_e32 v39, v39
	v_add_f32_e32 v76, v76, v144
	v_add_f32_e32 v40, v40, v154
	v_mul_f32_e32 v76, 0xbfb8aa3b, v76
	v_mul_f32_e32 v40, 0xbfb8aa3b, v40
	v_exp_f32_e32 v76, v76
	v_exp_f32_e32 v40, v40
	v_add_f32_e32 v77, v77, v144
	v_add_f32_e32 v41, v41, v154
	v_mul_f32_e32 v77, 0xbfb8aa3b, v77
	v_mul_f32_e32 v41, 0xbfb8aa3b, v41
	v_exp_f32_e32 v77, v77
	v_exp_f32_e32 v41, v41
	v_pk_add_f32 v[78:79], v[78:79], 1.0 op_sel_hi:[1,0]
	v_pk_add_f32 v[46:47], v[46:47], 1.0 op_sel_hi:[1,0]
	v_lshlrev_b32_e32 v156, 16, v230
	v_and_b32_e32 v157, 0xffff0000, v230
	v_rcp_f32_e32 v78, v78
	v_rcp_f32_e32 v79, v79
	v_lshlrev_b32_e32 v164, 16, v246
	v_and_b32_e32 v165, 0xffff0000, v246
	v_rcp_f32_e32 v46, v46
	v_rcp_f32_e32 v47, v47
	v_pk_mul_f32 v[78:79], v[78:79], v[156:157]
	s_nop 0
	v_pk_fma_f32 v[78:79], v[46:47], v[164:165], v[78:79]
	v_pk_add_f32 v[80:81], v[80:81], 1.0 op_sel_hi:[1,0]
	v_pk_add_f32 v[48:49], v[48:49], 1.0 op_sel_hi:[1,0]
	v_lshlrev_b32_e32 v156, 16, v231
	v_and_b32_e32 v157, 0xffff0000, v231
	v_rcp_f32_e32 v80, v80
	v_rcp_f32_e32 v81, v81
	v_lshlrev_b32_e32 v164, 16, v247
	v_and_b32_e32 v165, 0xffff0000, v247
	v_rcp_f32_e32 v48, v48
	v_rcp_f32_e32 v49, v49
	v_pk_mul_f32 v[80:81], v[80:81], v[156:157]
	s_nop 0
	v_pk_fma_f32 v[80:81], v[48:49], v[164:165], v[80:81]
	v_pk_add_f32 v[74:75], v[74:75], 1.0 op_sel_hi:[1,0]
	v_pk_add_f32 v[38:39], v[38:39], 1.0 op_sel_hi:[1,0]
	v_lshlrev_b32_e32 v156, 16, v232
	v_and_b32_e32 v157, 0xffff0000, v232
	v_rcp_f32_e32 v74, v74
	v_rcp_f32_e32 v75, v75
	v_lshlrev_b32_e32 v164, 16, v248
	v_and_b32_e32 v165, 0xffff0000, v248
	v_rcp_f32_e32 v38, v38
	v_rcp_f32_e32 v39, v39
	v_pk_mul_f32 v[74:75], v[74:75], v[156:157]
	s_nop 0
	v_pk_fma_f32 v[74:75], v[38:39], v[164:165], v[74:75]
	v_pk_add_f32 v[76:77], v[76:77], 1.0 op_sel_hi:[1,0]
	v_pk_add_f32 v[40:41], v[40:41], 1.0 op_sel_hi:[1,0]
	v_lshlrev_b32_e32 v156, 16, v233
	v_and_b32_e32 v157, 0xffff0000, v233
	v_rcp_f32_e32 v76, v76
	v_rcp_f32_e32 v77, v77
	v_lshlrev_b32_e32 v164, 16, v249
	v_and_b32_e32 v165, 0xffff0000, v249
	v_rcp_f32_e32 v40, v40
	v_rcp_f32_e32 v41, v41
	v_pk_mul_f32 v[76:77], v[76:77], v[156:157]
	s_nop 0
	v_pk_fma_f32 v[76:77], v[40:41], v[164:165], v[76:77]
	v_cvt_pk_bf16_f32 v230, v78, v79
	v_cvt_pk_bf16_f32 v231, v80, v81
	v_cvt_pk_bf16_f32 v232, v74, v75
	v_cvt_pk_bf16_f32 v233, v76, v77
	global_store_dwordx4 v0, v[230:233], s[44:45] offset:0
	s_waitcnt vmcnt(9)
	v_add_f32_e32 v70, v70, v143
	v_add_f32_e32 v34, v34, v145
	v_mul_f32_e32 v70, 0xbfb8aa3b, v70
	v_mul_f32_e32 v34, 0xbfb8aa3b, v34
	v_exp_f32_e32 v70, v70
	v_exp_f32_e32 v34, v34
	v_add_f32_e32 v71, v71, v143
	v_add_f32_e32 v35, v35, v145
	v_mul_f32_e32 v71, 0xbfb8aa3b, v71
	v_mul_f32_e32 v35, 0xbfb8aa3b, v35
	v_exp_f32_e32 v71, v71
	v_exp_f32_e32 v35, v35
	v_add_f32_e32 v72, v72, v143
	v_add_f32_e32 v36, v36, v145
	v_mul_f32_e32 v72, 0xbfb8aa3b, v72
	v_mul_f32_e32 v36, 0xbfb8aa3b, v36
	v_exp_f32_e32 v72, v72
	v_exp_f32_e32 v36, v36
	v_add_f32_e32 v73, v73, v143
	v_add_f32_e32 v37, v37, v145
	v_mul_f32_e32 v73, 0xbfb8aa3b, v73
	v_mul_f32_e32 v37, 0xbfb8aa3b, v37
	v_exp_f32_e32 v73, v73
	v_exp_f32_e32 v37, v37
	v_add_f32_e32 v66, v66, v144
	v_add_f32_e32 v26, v26, v154
	v_mul_f32_e32 v66, 0xbfb8aa3b, v66
	v_mul_f32_e32 v26, 0xbfb8aa3b, v26
	v_exp_f32_e32 v66, v66
	v_exp_f32_e32 v26, v26
	v_add_f32_e32 v67, v67, v144
	v_add_f32_e32 v27, v27, v154
	v_mul_f32_e32 v67, 0xbfb8aa3b, v67
	v_mul_f32_e32 v27, 0xbfb8aa3b, v27
	v_exp_f32_e32 v67, v67
	v_exp_f32_e32 v27, v27
	v_add_f32_e32 v68, v68, v144
	v_add_f32_e32 v28, v28, v154
	v_mul_f32_e32 v68, 0xbfb8aa3b, v68
	v_mul_f32_e32 v28, 0xbfb8aa3b, v28
	v_exp_f32_e32 v68, v68
	v_exp_f32_e32 v28, v28
	v_add_f32_e32 v69, v69, v144
	v_add_f32_e32 v29, v29, v154
	v_mul_f32_e32 v69, 0xbfb8aa3b, v69
	v_mul_f32_e32 v29, 0xbfb8aa3b, v29
	v_exp_f32_e32 v69, v69
	v_exp_f32_e32 v29, v29
	v_pk_add_f32 v[70:71], v[70:71], 1.0 op_sel_hi:[1,0]
	v_pk_add_f32 v[34:35], v[34:35], 1.0 op_sel_hi:[1,0]
	v_lshlrev_b32_e32 v156, 16, v234
	v_and_b32_e32 v157, 0xffff0000, v234
	v_rcp_f32_e32 v70, v70
	v_rcp_f32_e32 v71, v71
	v_lshlrev_b32_e32 v164, 16, v250
	v_and_b32_e32 v165, 0xffff0000, v250
	v_rcp_f32_e32 v34, v34
	v_rcp_f32_e32 v35, v35
	v_pk_mul_f32 v[70:71], v[70:71], v[156:157]
	s_nop 0
	v_pk_fma_f32 v[70:71], v[34:35], v[164:165], v[70:71]
	v_pk_add_f32 v[72:73], v[72:73], 1.0 op_sel_hi:[1,0]
	v_pk_add_f32 v[36:37], v[36:37], 1.0 op_sel_hi:[1,0]
	v_lshlrev_b32_e32 v156, 16, v235
	v_and_b32_e32 v157, 0xffff0000, v235
	v_rcp_f32_e32 v72, v72
	v_rcp_f32_e32 v73, v73
	v_lshlrev_b32_e32 v164, 16, v251
	v_and_b32_e32 v165, 0xffff0000, v251
	v_rcp_f32_e32 v36, v36
	v_rcp_f32_e32 v37, v37
	v_pk_mul_f32 v[72:73], v[72:73], v[156:157]
	s_nop 0
	v_pk_fma_f32 v[72:73], v[36:37], v[164:165], v[72:73]
	v_pk_add_f32 v[66:67], v[66:67], 1.0 op_sel_hi:[1,0]
	v_pk_add_f32 v[26:27], v[26:27], 1.0 op_sel_hi:[1,0]
	v_lshlrev_b32_e32 v156, 16, v236
	v_and_b32_e32 v157, 0xffff0000, v236
	v_rcp_f32_e32 v66, v66
	v_rcp_f32_e32 v67, v67
	v_lshlrev_b32_e32 v164, 16, v252
	v_and_b32_e32 v165, 0xffff0000, v252
	v_rcp_f32_e32 v26, v26
	v_rcp_f32_e32 v27, v27
	v_pk_mul_f32 v[66:67], v[66:67], v[156:157]
	s_nop 0
	v_pk_fma_f32 v[66:67], v[26:27], v[164:165], v[66:67]
	v_pk_add_f32 v[68:69], v[68:69], 1.0 op_sel_hi:[1,0]
	v_pk_add_f32 v[28:29], v[28:29], 1.0 op_sel_hi:[1,0]
	v_lshlrev_b32_e32 v156, 16, v237
	v_and_b32_e32 v157, 0xffff0000, v237
	v_rcp_f32_e32 v68, v68
	v_rcp_f32_e32 v69, v69
	v_lshlrev_b32_e32 v164, 16, v253
	v_and_b32_e32 v165, 0xffff0000, v253
	v_rcp_f32_e32 v28, v28
	v_rcp_f32_e32 v29, v29
	v_pk_mul_f32 v[68:69], v[68:69], v[156:157]
	s_nop 0
	v_pk_fma_f32 v[68:69], v[28:29], v[164:165], v[68:69]
	v_cvt_pk_bf16_f32 v234, v70, v71
	v_cvt_pk_bf16_f32 v235, v72, v73
	v_cvt_pk_bf16_f32 v236, v66, v67
	v_cvt_pk_bf16_f32 v237, v68, v69
	global_store_dwordx4 v0, v[234:237], s[44:45] offset:1024
	s_waitcnt vmcnt(8)
; DI float sigm(float x) { return 1.f / (1.f + __expf(-x)); }
; DI u32x4 pack8(const float* f) { u32x4 o; o.x = pack2(f[0], f[1]); o.y = pack2(f[2], f[3]); o.z = pack2(f[4], f[5]); o.w = pack2(f[6], f[7]); return o; }
; DI int tid512() { int t = threadIdx.x; asm volatile("" : "+v"(t)); return t; }
; DI u32x4* merge_scratch(PREF p, int region) { const int t = tid512(); return (u32x4*)p.fbuf + (size_t)blockIdx.x * 40960 + region * 8192 + (t >> 6) * 1024 + (t & 63); }
; DI void gate_reg(PREF p, int l, int n, f32x4 (&acc)[2][2][4][2], int dt) {
;   const u32x4* sbn = merge_scratch(p, n);
;   u32x4* ssum = merge_scratch(p, 4);
;   const int t = tid512(), wid = t >> 6, lane = t & 63, wc = wid & 3, fr = lane & 15;
;   const float* bm = p.b_merge + (size_t)l * 4096 + n * 1024 + dt * 256 + wc * 32 + fr;
;   float bias[2][2];
; #pragma unroll
;   for (int bj = 0; bj < 2; ++bj)
; #pragma unroll
;     for (int nn = 0; nn < 2; ++nn) bias[bj][nn] = bm[bj * 128 + nn * 16];
; #pragma unroll
;   for (int ai = 0; ai < 2; ++ai)
; #pragma unroll
;     for (int bj = 0; bj < 2; ++bj) {
;       __builtin_amdgcn_sched_barrier(0);
;       u32x4 bn[4], pv[4];
; #pragma unroll
;       for (int m = 0; m < 4; ++m) {
;         bn[m] = sbn[((ai * 2 + bj) * 4 + m) * 64];
;         if (n > 0) pv[m] = ssum[((ai * 2 + bj) * 4 + m) * 64];
;       }
; #pragma unroll
;       for (int m = 0; m < 4; ++m) {
;         float b[8]; unpack8(bn[m], b);
;         float v[8];
; #pragma unroll
;         for (int nn = 0; nn < 2; ++nn)
; #pragma unroll
;           for (int j = 0; j < 4; ++j) v[nn * 4 + j] = sigm(acc[ai][bj][m][nn][j] + bias[bj][nn]) * b[nn * 4 + j];
;         if (n > 0) {
;           float o[8]; unpack8(pv[m], o);
; #pragma unroll
;           for (int e = 0; e < 8; ++e) v[e] += o[e];
;         }
;         if (n < 3) ssum[((ai * 2 + bj) * 4 + m) * 64] = pack8(v);
; #pragma unroll
;         for (int nn = 0; nn < 2; ++nn)
; #pragma unroll
;           for (int j = 0; j < 4; ++j) acc[ai][bj][m][nn][j] = v[nn * 4 + j];
;       }
;     }
; }
	v_add_f32_e32 v62, v62, v143
	v_add_f32_e32 v22, v22, v145
	v_mul_f32_e32 v62, 0xbfb8aa3b, v62
	v_mul_f32_e32 v22, 0xbfb8aa3b, v22
	v_exp_f32_e32 v62, v62
	v_exp_f32_e32 v22, v22
	v_add_f32_e32 v63, v63, v143
	v_add_f32_e32 v23, v23, v145
	v_mul_f32_e32 v63, 0xbfb8aa3b, v63
	v_mul_f32_e32 v23, 0xbfb8aa3b, v23
	v_exp_f32_e32 v63, v63
	v_exp_f32_e32 v23, v23
	v_add_f32_e32 v64, v64, v143
	v_add_f32_e32 v24, v24, v145
	v_mul_f32_e32 v64, 0xbfb8aa3b, v64
	v_mul_f32_e32 v24, 0xbfb8aa3b, v24
	v_exp_f32_e32 v64, v64
	v_exp_f32_e32 v24, v24
	v_add_f32_e32 v65, v65, v143
	v_add_f32_e32 v25, v25, v145
	v_mul_f32_e32 v65, 0xbfb8aa3b, v65
	v_mul_f32_e32 v25, 0xbfb8aa3b, v25
	v_exp_f32_e32 v65, v65
	v_exp_f32_e32 v25, v25
	v_add_f32_e32 v58, v58, v144
	v_add_f32_e32 v14, v14, v154
	v_mul_f32_e32 v58, 0xbfb8aa3b, v58
	v_mul_f32_e32 v14, 0xbfb8aa3b, v14
	v_exp_f32_e32 v58, v58
	v_exp_f32_e32 v14, v14
	v_add_f32_e32 v59, v59, v144
	v_add_f32_e32 v15, v15, v154
	v_mul_f32_e32 v59, 0xbfb8aa3b, v59
	v_mul_f32_e32 v15, 0xbfb8aa3b, v15
	v_exp_f32_e32 v59, v59
	v_exp_f32_e32 v15, v15
	v_add_f32_e32 v60, v60, v144
	v_add_f32_e32 v16, v16, v154
	v_mul_f32_e32 v60, 0xbfb8aa3b, v60
	v_mul_f32_e32 v16, 0xbfb8aa3b, v16
	v_exp_f32_e32 v60, v60
	v_exp_f32_e32 v16, v16
	v_add_f32_e32 v61, v61, v144
	v_add_f32_e32 v17, v17, v154
	v_mul_f32_e32 v61, 0xbfb8aa3b, v61
	v_mul_f32_e32 v17, 0xbfb8aa3b, v17
	v_exp_f32_e32 v61, v61
	v_exp_f32_e32 v17, v17
	v_pk_add_f32 v[62:63], v[62:63], 1.0 op_sel_hi:[1,0]
	v_pk_add_f32 v[22:23], v[22:23], 1.0 op_sel_hi:[1,0]
	v_lshlrev_b32_e32 v156, 16, v238
	v_and_b32_e32 v157, 0xffff0000, v238
	v_rcp_f32_e32 v62, v62
	v_rcp_f32_e32 v63, v63
	v_lshlrev_b32_e32 v164, 16, v6
	v_and_b32_e32 v165, 0xffff0000, v6
	v_rcp_f32_e32 v22, v22
	v_rcp_f32_e32 v23, v23
	v_pk_mul_f32 v[62:63], v[62:63], v[156:157]
	s_nop 0
	v_pk_fma_f32 v[62:63], v[22:23], v[164:165], v[62:63]
	v_pk_add_f32 v[64:65], v[64:65], 1.0 op_sel_hi:[1,0]
	v_pk_add_f32 v[24:25], v[24:25], 1.0 op_sel_hi:[1,0]
	v_lshlrev_b32_e32 v156, 16, v239
	v_and_b32_e32 v157, 0xffff0000, v239
	v_rcp_f32_e32 v64, v64
	v_rcp_f32_e32 v65, v65
	v_lshlrev_b32_e32 v164, 16, v7
	v_and_b32_e32 v165, 0xffff0000, v7
	v_rcp_f32_e32 v24, v24
	v_rcp_f32_e32 v25, v25
	v_pk_mul_f32 v[64:65], v[64:65], v[156:157]
	s_nop 0
	v_pk_fma_f32 v[64:65], v[24:25], v[164:165], v[64:65]
	v_pk_add_f32 v[58:59], v[58:59], 1.0 op_sel_hi:[1,0]
	v_pk_add_f32 v[14:15], v[14:15], 1.0 op_sel_hi:[1,0]
	v_lshlrev_b32_e32 v156, 16, v240
	v_and_b32_e32 v157, 0xffff0000, v240
	v_rcp_f32_e32 v58, v58
	v_rcp_f32_e32 v59, v59
	v_lshlrev_b32_e32 v164, 16, v8
	v_and_b32_e32 v165, 0xffff0000, v8
	v_rcp_f32_e32 v14, v14
	v_rcp_f32_e32 v15, v15
	v_pk_mul_f32 v[58:59], v[58:59], v[156:157]
	s_nop 0
	v_pk_fma_f32 v[58:59], v[14:15], v[164:165], v[58:59]
	v_pk_add_f32 v[60:61], v[60:61], 1.0 op_sel_hi:[1,0]
	v_pk_add_f32 v[16:17], v[16:17], 1.0 op_sel_hi:[1,0]
	v_lshlrev_b32_e32 v156, 16, v241
	v_and_b32_e32 v157, 0xffff0000, v241
	v_rcp_f32_e32 v60, v60
	v_rcp_f32_e32 v61, v61
	v_lshlrev_b32_e32 v164, 16, v9
	v_and_b32_e32 v165, 0xffff0000, v9
	v_rcp_f32_e32 v16, v16
	v_rcp_f32_e32 v17, v17
	v_pk_mul_f32 v[60:61], v[60:61], v[156:157]
	s_nop 0
	v_pk_fma_f32 v[60:61], v[16:17], v[164:165], v[60:61]
	v_cvt_pk_bf16_f32 v238, v62, v63
	v_cvt_pk_bf16_f32 v239, v64, v65
	v_cvt_pk_bf16_f32 v240, v58, v59
	v_cvt_pk_bf16_f32 v241, v60, v61
	global_store_dwordx4 v0, v[238:241], s[44:45] offset:2048
	s_waitcnt vmcnt(7)
	v_add_f32_e32 v54, v54, v143
	v_add_f32_e32 v10, v10, v145
	v_mul_f32_e32 v54, 0xbfb8aa3b, v54
	v_mul_f32_e32 v10, 0xbfb8aa3b, v10
	v_exp_f32_e32 v54, v54
	v_exp_f32_e32 v10, v10
	v_add_f32_e32 v55, v55, v143
	v_add_f32_e32 v11, v11, v145
	v_mul_f32_e32 v55, 0xbfb8aa3b, v55
	v_mul_f32_e32 v11, 0xbfb8aa3b, v11
	v_exp_f32_e32 v55, v55
	v_exp_f32_e32 v11, v11
	v_add_f32_e32 v56, v56, v143
	v_add_f32_e32 v12, v12, v145
	v_mul_f32_e32 v56, 0xbfb8aa3b, v56
	v_mul_f32_e32 v12, 0xbfb8aa3b, v12
	v_exp_f32_e32 v56, v56
	v_exp_f32_e32 v12, v12
	v_add_f32_e32 v57, v57, v143
	v_add_f32_e32 v13, v13, v145
	v_mul_f32_e32 v57, 0xbfb8aa3b, v57
	v_mul_f32_e32 v13, 0xbfb8aa3b, v13
	v_exp_f32_e32 v57, v57
	v_exp_f32_e32 v13, v13
	v_add_f32_e32 v50, v50, v144
	v_add_f32_e32 v2, v2, v154
	v_mul_f32_e32 v50, 0xbfb8aa3b, v50
	v_mul_f32_e32 v2, 0xbfb8aa3b, v2
	v_exp_f32_e32 v50, v50
	v_exp_f32_e32 v2, v2
	v_add_f32_e32 v51, v51, v144
	v_add_f32_e32 v3, v3, v154
	v_mul_f32_e32 v51, 0xbfb8aa3b, v51
	v_mul_f32_e32 v3, 0xbfb8aa3b, v3
	v_exp_f32_e32 v51, v51
	v_exp_f32_e32 v3, v3
	v_add_f32_e32 v52, v52, v144
	v_add_f32_e32 v4, v4, v154
	v_mul_f32_e32 v52, 0xbfb8aa3b, v52
	v_mul_f32_e32 v4, 0xbfb8aa3b, v4
	v_exp_f32_e32 v52, v52
	v_exp_f32_e32 v4, v4
	v_add_f32_e32 v53, v53, v144
	v_add_f32_e32 v5, v5, v154
	v_mul_f32_e32 v53, 0xbfb8aa3b, v53
	v_mul_f32_e32 v5, 0xbfb8aa3b, v5
	v_exp_f32_e32 v53, v53
	v_exp_f32_e32 v5, v5
	v_pk_add_f32 v[54:55], v[54:55], 1.0 op_sel_hi:[1,0]
	v_pk_add_f32 v[10:11], v[10:11], 1.0 op_sel_hi:[1,0]
	v_lshlrev_b32_e32 v156, 16, v242
	v_and_b32_e32 v157, 0xffff0000, v242
	v_rcp_f32_e32 v54, v54
	v_rcp_f32_e32 v55, v55
	v_lshlrev_b32_e32 v164, 16, v18
	v_and_b32_e32 v165, 0xffff0000, v18
	v_rcp_f32_e32 v10, v10
	v_rcp_f32_e32 v11, v11
	v_pk_mul_f32 v[54:55], v[54:55], v[156:157]
	s_nop 0
	v_pk_fma_f32 v[54:55], v[10:11], v[164:165], v[54:55]
	v_pk_add_f32 v[56:57], v[56:57], 1.0 op_sel_hi:[1,0]
	v_pk_add_f32 v[12:13], v[12:13], 1.0 op_sel_hi:[1,0]
	v_lshlrev_b32_e32 v156, 16, v243
	v_and_b32_e32 v157, 0xffff0000, v243
	v_rcp_f32_e32 v56, v56
	v_rcp_f32_e32 v57, v57
	v_lshlrev_b32_e32 v164, 16, v19
	v_and_b32_e32 v165, 0xffff0000, v19
	v_rcp_f32_e32 v12, v12
	v_rcp_f32_e32 v13, v13
	v_pk_mul_f32 v[56:57], v[56:57], v[156:157]
	s_nop 0
	v_pk_fma_f32 v[56:57], v[12:13], v[164:165], v[56:57]
	v_pk_add_f32 v[50:51], v[50:51], 1.0 op_sel_hi:[1,0]
	v_pk_add_f32 v[2:3], v[2:3], 1.0 op_sel_hi:[1,0]
	v_lshlrev_b32_e32 v156, 16, v244
	v_and_b32_e32 v157, 0xffff0000, v244
	v_rcp_f32_e32 v50, v50
	v_rcp_f32_e32 v51, v51
	v_lshlrev_b32_e32 v164, 16, v20
	v_and_b32_e32 v165, 0xffff0000, v20
	v_rcp_f32_e32 v2, v2
	v_rcp_f32_e32 v3, v3
	v_pk_mul_f32 v[50:51], v[50:51], v[156:157]
	s_nop 0
	v_pk_fma_f32 v[50:51], v[2:3], v[164:165], v[50:51]
	v_pk_add_f32 v[52:53], v[52:53], 1.0 op_sel_hi:[1,0]
	v_pk_add_f32 v[4:5], v[4:5], 1.0 op_sel_hi:[1,0]
	v_lshlrev_b32_e32 v156, 16, v245
	v_and_b32_e32 v157, 0xffff0000, v245
	v_rcp_f32_e32 v52, v52
	v_rcp_f32_e32 v53, v53
	v_lshlrev_b32_e32 v164, 16, v21
	v_and_b32_e32 v165, 0xffff0000, v21
	v_rcp_f32_e32 v4, v4
	v_rcp_f32_e32 v5, v5
	v_pk_mul_f32 v[52:53], v[52:53], v[156:157]
	s_nop 0
	v_pk_fma_f32 v[52:53], v[4:5], v[164:165], v[52:53]
	v_cvt_pk_bf16_f32 v242, v54, v55
	v_cvt_pk_bf16_f32 v243, v56, v57
	v_cvt_pk_bf16_f32 v244, v50, v51
	v_cvt_pk_bf16_f32 v245, v52, v53
	global_store_dwordx4 v0, v[242:245], s[44:45] offset:3072
	s_branch .LBB0_101
; DI float sigm(float x) { return 1.f / (1.f + __expf(-x)); }
; DI u32x4 pack8(const float* f) { u32x4 o; o.x = pack2(f[0], f[1]); o.y = pack2(f[2], f[3]); o.z = pack2(f[4], f[5]); o.w = pack2(f[6], f[7]); return o; }
; DI int tid512() { int t = threadIdx.x; asm volatile("" : "+v"(t)); return t; }
; DI u32x4* merge_scratch(PREF p, int region) { const int t = tid512(); return (u32x4*)p.fbuf + (size_t)blockIdx.x * 40960 + region * 8192 + (t >> 6) * 1024 + (t & 63); }
; DI void gate_reg(PREF p, int l, int n, f32x4 (&acc)[2][2][4][2], int dt) {
;   const u32x4* sbn = merge_scratch(p, n);
;   u32x4* ssum = merge_scratch(p, 4);
;   const int t = tid512(), wid = t >> 6, lane = t & 63, wc = wid & 3, fr = lane & 15;
;   const float* bm = p.b_merge + (size_t)l * 4096 + n * 1024 + dt * 256 + wc * 32 + fr;
;   float bias[2][2];
; #pragma unroll
;   for (int bj = 0; bj < 2; ++bj)
; #pragma unroll
;     for (int nn = 0; nn < 2; ++nn) bias[bj][nn] = bm[bj * 128 + nn * 16];
; #pragma unroll
;   for (int ai = 0; ai < 2; ++ai)
; #pragma unroll
;     for (int bj = 0; bj < 2; ++bj) {
;       __builtin_amdgcn_sched_barrier(0);
;       u32x4 bn[4], pv[4];
; #pragma unroll
;       for (int m = 0; m < 4; ++m) {
;         bn[m] = sbn[((ai * 2 + bj) * 4 + m) * 64];
;         if (n > 0) pv[m] = ssum[((ai * 2 + bj) * 4 + m) * 64];
;       }
; #pragma unroll
;       for (int m = 0; m < 4; ++m) {
;         float b[8]; unpack8(bn[m], b);
;         float v[8];
; #pragma unroll
;         for (int nn = 0; nn < 2; ++nn)
; #pragma unroll
;           for (int j = 0; j < 4; ++j) v[nn * 4 + j] = sigm(acc[ai][bj][m][nn][j] + bias[bj][nn]) * b[nn * 4 + j];
;         if (n > 0) {
;           float o[8]; unpack8(pv[m], o);
; #pragma unroll
;           for (int e = 0; e < 8; ++e) v[e] += o[e];
;         }
;         if (n < 3) ssum[((ai * 2 + bj) * 4 + m) * 64] = pack8(v);
; #pragma unroll
;         for (int nn = 0; nn < 2; ++nn)
; #pragma unroll
;           for (int j = 0; j < 4; ++j) acc[ai][bj][m][nn][j] = v[nn * 4 + j];
;       }
;     }
; }
.Lmy_gp_p1:
	global_load_dword v143, v155, s[98:99]
	global_load_dword v144, v155, s[98:99] offset:64
	global_load_dword v145, v155, s[0:1]
	global_load_dword v154, v155, s[0:1] offset:64
	global_load_dwordx4 v[182:185], v142, s[8:9] offset:0
	global_load_dwordx4 v[198:201], v142, s[10:11] offset:0
	global_load_dwordx4 v[214:217], v142, s[44:45] offset:0
	global_load_dwordx4 v[186:189], v142, s[8:9] offset:1024
	global_load_dwordx4 v[202:205], v142, s[10:11] offset:1024
	global_load_dwordx4 v[218:221], v142, s[44:45] offset:1024
	global_load_dwordx4 v[190:193], v142, s[8:9] offset:2048
	global_load_dwordx4 v[206:209], v142, s[10:11] offset:2048
	global_load_dwordx4 v[222:225], v142, s[44:45] offset:2048
	global_load_dwordx4 v[194:197], v142, s[8:9] offset:3072
	global_load_dwordx4 v[210:213], v142, s[10:11] offset:3072
	global_load_dwordx4 v[226:229], v142, s[44:45] offset:3072
	global_load_dwordx4 v[230:233], v0, s[8:9] offset:0
	global_load_dwordx4 v[246:249], v0, s[10:11] offset:0
	global_load_dwordx4 v[30:33], v0, s[44:45] offset:0
	global_load_dwordx4 v[234:237], v0, s[8:9] offset:1024
	global_load_dwordx4 v[250:253], v0, s[10:11] offset:1024
	global_load_dwordx4 v[42:45], v0, s[44:45] offset:1024
	global_load_dwordx4 v[238:241], v0, s[8:9] offset:2048
	global_load_dwordx4 v[6:9], v0, s[10:11] offset:2048
	global_load_dwordx4 v[118:121], v0, s[44:45] offset:2048
	global_load_dwordx4 v[242:245], v0, s[8:9] offset:3072
	global_load_dwordx4 v[18:21], v0, s[10:11] offset:3072
	global_load_dwordx4 v[130:133], v0, s[44:45] offset:3072
	s_waitcnt vmcnt(21)
	v_add_f32_e32 v158, v158, v143
	v_add_f32_e32 v110, v110, v145
	v_mul_f32_e32 v158, 0xbfb8aa3b, v158
	v_mul_f32_e32 v110, 0xbfb8aa3b, v110
	v_exp_f32_e32 v158, v158
	v_exp_f32_e32 v110, v110
	v_add_f32_e32 v159, v159, v143
	v_add_f32_e32 v111, v111, v145
	v_mul_f32_e32 v159, 0xbfb8aa3b, v159
	v_mul_f32_e32 v111, 0xbfb8aa3b, v111
	v_exp_f32_e32 v159, v159
	v_exp_f32_e32 v111, v111
	v_add_f32_e32 v160, v160, v143
	v_add_f32_e32 v112, v112, v145
	v_mul_f32_e32 v160, 0xbfb8aa3b, v160
	v_mul_f32_e32 v112, 0xbfb8aa3b, v112
	v_exp_f32_e32 v160, v160
	v_exp_f32_e32 v112, v112
	v_add_f32_e32 v161, v161, v143
	v_add_f32_e32 v113, v113, v145
	v_mul_f32_e32 v161, 0xbfb8aa3b, v161
	v_mul_f32_e32 v113, 0xbfb8aa3b, v113
	v_exp_f32_e32 v161, v161
	v_exp_f32_e32 v113, v113
	v_add_f32_e32 v150, v150, v144
	v_add_f32_e32 v106, v106, v154
	v_mul_f32_e32 v150, 0xbfb8aa3b, v150
	v_mul_f32_e32 v106, 0xbfb8aa3b, v106
	v_exp_f32_e32 v150, v150
	v_exp_f32_e32 v106, v106
	v_add_f32_e32 v151, v151, v144
	v_add_f32_e32 v107, v107, v154
	v_mul_f32_e32 v151, 0xbfb8aa3b, v151
	v_mul_f32_e32 v107, 0xbfb8aa3b, v107
	v_exp_f32_e32 v151, v151
	v_exp_f32_e32 v107, v107
	v_add_f32_e32 v152, v152, v144
	v_add_f32_e32 v108, v108, v154
	v_mul_f32_e32 v152, 0xbfb8aa3b, v152
	v_mul_f32_e32 v108, 0xbfb8aa3b, v108
	v_exp_f32_e32 v152, v152
	v_exp_f32_e32 v108, v108
	v_add_f32_e32 v153, v153, v144
	v_add_f32_e32 v109, v109, v154
	v_mul_f32_e32 v153, 0xbfb8aa3b, v153
	v_mul_f32_e32 v109, 0xbfb8aa3b, v109
	v_exp_f32_e32 v153, v153
	v_exp_f32_e32 v109, v109
	v_pk_add_f32 v[158:159], v[158:159], 1.0 op_sel_hi:[1,0]
	v_pk_add_f32 v[110:111], v[110:111], 1.0 op_sel_hi:[1,0]
	v_lshlrev_b32_e32 v156, 16, v182
	v_and_b32_e32 v157, 0xffff0000, v182
	v_rcp_f32_e32 v158, v158
	v_rcp_f32_e32 v159, v159
	v_lshlrev_b32_e32 v164, 16, v198
	v_and_b32_e32 v165, 0xffff0000, v198
	v_rcp_f32_e32 v110, v110
	v_rcp_f32_e32 v111, v111
	v_pk_mul_f32 v[158:159], v[158:159], v[156:157]
	s_nop 0
	v_pk_fma_f32 v[158:159], v[110:111], v[164:165], v[158:159]
	v_lshlrev_b32_e32 v166, 16, v214
	v_and_b32_e32 v167, 0xffff0000, v214
	v_pk_add_f32 v[158:159], v[158:159], v[166:167]
	v_pk_add_f32 v[160:161], v[160:161], 1.0 op_sel_hi:[1,0]
	v_pk_add_f32 v[112:113], v[112:113], 1.0 op_sel_hi:[1,0]
	v_lshlrev_b32_e32 v156, 16, v183
	v_and_b32_e32 v157, 0xffff0000, v183
	v_rcp_f32_e32 v160, v160
	v_rcp_f32_e32 v161, v161
	v_lshlrev_b32_e32 v164, 16, v199
	v_and_b32_e32 v165, 0xffff0000, v199
	v_rcp_f32_e32 v112, v112
	v_rcp_f32_e32 v113, v113
	v_pk_mul_f32 v[160:161], v[160:161], v[156:157]
	s_nop 0
	v_pk_fma_f32 v[160:161], v[112:113], v[164:165], v[160:161]
	v_lshlrev_b32_e32 v166, 16, v215
	v_and_b32_e32 v167, 0xffff0000, v215
	v_pk_add_f32 v[160:161], v[160:161], v[166:167]
	v_pk_add_f32 v[150:151], v[150:151], 1.0 op_sel_hi:[1,0]
	v_pk_add_f32 v[106:107], v[106:107], 1.0 op_sel_hi:[1,0]
	v_lshlrev_b32_e32 v156, 16, v184
	v_and_b32_e32 v157, 0xffff0000, v184
	v_rcp_f32_e32 v150, v150
	v_rcp_f32_e32 v151, v151
	v_lshlrev_b32_e32 v164, 16, v200
	v_and_b32_e32 v165, 0xffff0000, v200
	v_rcp_f32_e32 v106, v106
	v_rcp_f32_e32 v107, v107
	v_pk_mul_f32 v[150:151], v[150:151], v[156:157]
	s_nop 0
	v_pk_fma_f32 v[150:151], v[106:107], v[164:165], v[150:151]
	v_lshlrev_b32_e32 v166, 16, v216
	v_and_b32_e32 v167, 0xffff0000, v216
	v_pk_add_f32 v[150:151], v[150:151], v[166:167]
	v_pk_add_f32 v[152:153], v[152:153], 1.0 op_sel_hi:[1,0]
	v_pk_add_f32 v[108:109], v[108:109], 1.0 op_sel_hi:[1,0]
	v_lshlrev_b32_e32 v156, 16, v185
	v_and_b32_e32 v157, 0xffff0000, v185
	v_rcp_f32_e32 v152, v152
	v_rcp_f32_e32 v153, v153
	v_lshlrev_b32_e32 v164, 16, v201
	v_and_b32_e32 v165, 0xffff0000, v201
	v_rcp_f32_e32 v108, v108
	v_rcp_f32_e32 v109, v109
	v_pk_mul_f32 v[152:153], v[152:153], v[156:157]
	s_nop 0
	v_pk_fma_f32 v[152:153], v[108:109], v[164:165], v[152:153]
	v_lshlrev_b32_e32 v166, 16, v217
	v_and_b32_e32 v167, 0xffff0000, v217
	v_pk_add_f32 v[152:153], v[152:153], v[166:167]
	s_waitcnt vmcnt(18)
; DI float sigm(float x) { return 1.f / (1.f + __expf(-x)); }
; DI u32x4 pack8(const float* f) { u32x4 o; o.x = pack2(f[0], f[1]); o.y = pack2(f[2], f[3]); o.z = pack2(f[4], f[5]); o.w = pack2(f[6], f[7]); return o; }
; DI int tid512() { int t = threadIdx.x; asm volatile("" : "+v"(t)); return t; }
; DI u32x4* merge_scratch(PREF p, int region) { const int t = tid512(); return (u32x4*)p.fbuf + (size_t)blockIdx.x * 40960 + region * 8192 + (t >> 6) * 1024 + (t & 63); }
; DI void gate_reg(PREF p, int l, int n, f32x4 (&acc)[2][2][4][2], int dt) {
;   const u32x4* sbn = merge_scratch(p, n);
;   u32x4* ssum = merge_scratch(p, 4);
;   const int t = tid512(), wid = t >> 6, lane = t & 63, wc = wid & 3, fr = lane & 15;
;   const float* bm = p.b_merge + (size_t)l * 4096 + n * 1024 + dt * 256 + wc * 32 + fr;
;   float bias[2][2];
; #pragma unroll
;   for (int bj = 0; bj < 2; ++bj)
; #pragma unroll
;     for (int nn = 0; nn < 2; ++nn) bias[bj][nn] = bm[bj * 128 + nn * 16];
; #pragma unroll
;   for (int ai = 0; ai < 2; ++ai)
; #pragma unroll
;     for (int bj = 0; bj < 2; ++bj) {
;       __builtin_amdgcn_sched_barrier(0);
;       u32x4 bn[4], pv[4];
; #pragma unroll
;       for (int m = 0; m < 4; ++m) {
;         bn[m] = sbn[((ai * 2 + bj) * 4 + m) * 64];
;         if (n > 0) pv[m] = ssum[((ai * 2 + bj) * 4 + m) * 64];
;       }
; #pragma unroll
;       for (int m = 0; m < 4; ++m) {
;         float b[8]; unpack8(bn[m], b);
;         float v[8];
; #pragma unroll
;         for (int nn = 0; nn < 2; ++nn)
; #pragma unroll
;           for (int j = 0; j < 4; ++j) v[nn * 4 + j] = sigm(acc[ai][bj][m][nn][j] + bias[bj][nn]) * b[nn * 4 + j];
;         if (n > 0) {
;           float o[8]; unpack8(pv[m], o);
; #pragma unroll
;           for (int e = 0; e < 8; ++e) v[e] += o[e];
;         }
;         if (n < 3) ssum[((ai * 2 + bj) * 4 + m) * 64] = pack8(v);
; #pragma unroll
;         for (int nn = 0; nn < 2; ++nn)
; #pragma unroll
;           for (int j = 0; j < 4; ++j) acc[ai][bj][m][nn][j] = v[nn * 4 + j];
;       }
;     }
; }
	v_add_f32_e32 v146, v146, v143
	v_add_f32_e32 v102, v102, v145
	v_mul_f32_e32 v146, 0xbfb8aa3b, v146
	v_mul_f32_e32 v102, 0xbfb8aa3b, v102
	v_exp_f32_e32 v146, v146
	v_exp_f32_e32 v102, v102
	v_add_f32_e32 v147, v147, v143
	v_add_f32_e32 v103, v103, v145
	v_mul_f32_e32 v147, 0xbfb8aa3b, v147
	v_mul_f32_e32 v103, 0xbfb8aa3b, v103
	v_exp_f32_e32 v147, v147
	v_exp_f32_e32 v103, v103
	v_add_f32_e32 v148, v148, v143
	v_add_f32_e32 v104, v104, v145
	v_mul_f32_e32 v148, 0xbfb8aa3b, v148
	v_mul_f32_e32 v104, 0xbfb8aa3b, v104
	v_exp_f32_e32 v148, v148
	v_exp_f32_e32 v104, v104
	v_add_f32_e32 v149, v149, v143
	v_add_f32_e32 v105, v105, v145
	v_mul_f32_e32 v149, 0xbfb8aa3b, v149
	v_mul_f32_e32 v105, 0xbfb8aa3b, v105
	v_exp_f32_e32 v149, v149
	v_exp_f32_e32 v105, v105
	v_add_f32_e32 v138, v138, v144
	v_add_f32_e32 v98, v98, v154
	v_mul_f32_e32 v138, 0xbfb8aa3b, v138
	v_mul_f32_e32 v98, 0xbfb8aa3b, v98
	v_exp_f32_e32 v138, v138
	v_exp_f32_e32 v98, v98
	v_add_f32_e32 v139, v139, v144
	v_add_f32_e32 v99, v99, v154
	v_mul_f32_e32 v139, 0xbfb8aa3b, v139
	v_mul_f32_e32 v99, 0xbfb8aa3b, v99
	v_exp_f32_e32 v139, v139
	v_exp_f32_e32 v99, v99
	v_add_f32_e32 v140, v140, v144
	v_add_f32_e32 v100, v100, v154
	v_mul_f32_e32 v140, 0xbfb8aa3b, v140
	v_mul_f32_e32 v100, 0xbfb8aa3b, v100
	v_exp_f32_e32 v140, v140
	v_exp_f32_e32 v100, v100
	v_add_f32_e32 v141, v141, v144
	v_add_f32_e32 v101, v101, v154
	v_mul_f32_e32 v141, 0xbfb8aa3b, v141
	v_mul_f32_e32 v101, 0xbfb8aa3b, v101
	v_exp_f32_e32 v141, v141
	v_exp_f32_e32 v101, v101
	v_pk_add_f32 v[146:147], v[146:147], 1.0 op_sel_hi:[1,0]
	v_pk_add_f32 v[102:103], v[102:103], 1.0 op_sel_hi:[1,0]
	v_lshlrev_b32_e32 v156, 16, v186
	v_and_b32_e32 v157, 0xffff0000, v186
	v_rcp_f32_e32 v146, v146
	v_rcp_f32_e32 v147, v147
	v_lshlrev_b32_e32 v164, 16, v202
	v_and_b32_e32 v165, 0xffff0000, v202
	v_rcp_f32_e32 v102, v102
	v_rcp_f32_e32 v103, v103
	v_pk_mul_f32 v[146:147], v[146:147], v[156:157]
	s_nop 0
	v_pk_fma_f32 v[146:147], v[102:103], v[164:165], v[146:147]
	v_lshlrev_b32_e32 v166, 16, v218
	v_and_b32_e32 v167, 0xffff0000, v218
	v_pk_add_f32 v[146:147], v[146:147], v[166:167]
	v_pk_add_f32 v[148:149], v[148:149], 1.0 op_sel_hi:[1,0]
	v_pk_add_f32 v[104:105], v[104:105], 1.0 op_sel_hi:[1,0]
	v_lshlrev_b32_e32 v156, 16, v187
	v_and_b32_e32 v157, 0xffff0000, v187
	v_rcp_f32_e32 v148, v148
	v_rcp_f32_e32 v149, v149
	v_lshlrev_b32_e32 v164, 16, v203
	v_and_b32_e32 v165, 0xffff0000, v203
	v_rcp_f32_e32 v104, v104
	v_rcp_f32_e32 v105, v105
	v_pk_mul_f32 v[148:149], v[148:149], v[156:157]
	s_nop 0
	v_pk_fma_f32 v[148:149], v[104:105], v[164:165], v[148:149]
	v_lshlrev_b32_e32 v166, 16, v219
	v_and_b32_e32 v167, 0xffff0000, v219
	v_pk_add_f32 v[148:149], v[148:149], v[166:167]
	v_pk_add_f32 v[138:139], v[138:139], 1.0 op_sel_hi:[1,0]
	v_pk_add_f32 v[98:99], v[98:99], 1.0 op_sel_hi:[1,0]
	v_lshlrev_b32_e32 v156, 16, v188
	v_and_b32_e32 v157, 0xffff0000, v188
	v_rcp_f32_e32 v138, v138
	v_rcp_f32_e32 v139, v139
	v_lshlrev_b32_e32 v164, 16, v204
	v_and_b32_e32 v165, 0xffff0000, v204
	v_rcp_f32_e32 v98, v98
	v_rcp_f32_e32 v99, v99
	v_pk_mul_f32 v[138:139], v[138:139], v[156:157]
	s_nop 0
	v_pk_fma_f32 v[138:139], v[98:99], v[164:165], v[138:139]
	v_lshlrev_b32_e32 v166, 16, v220
	v_and_b32_e32 v167, 0xffff0000, v220
	v_pk_add_f32 v[138:139], v[138:139], v[166:167]
	v_pk_add_f32 v[140:141], v[140:141], 1.0 op_sel_hi:[1,0]
	v_pk_add_f32 v[100:101], v[100:101], 1.0 op_sel_hi:[1,0]
	v_lshlrev_b32_e32 v156, 16, v189
	v_and_b32_e32 v157, 0xffff0000, v189
	v_rcp_f32_e32 v140, v140
	v_rcp_f32_e32 v141, v141
	v_lshlrev_b32_e32 v164, 16, v205
	v_and_b32_e32 v165, 0xffff0000, v205
	v_rcp_f32_e32 v100, v100
	v_rcp_f32_e32 v101, v101
	v_pk_mul_f32 v[140:141], v[140:141], v[156:157]
	s_nop 0
	v_pk_fma_f32 v[140:141], v[100:101], v[164:165], v[140:141]
	v_lshlrev_b32_e32 v166, 16, v221
	v_and_b32_e32 v167, 0xffff0000, v221
	v_pk_add_f32 v[140:141], v[140:141], v[166:167]
	s_waitcnt vmcnt(15)
	v_add_f32_e32 v134, v134, v143
	v_add_f32_e32 v94, v94, v145
	v_mul_f32_e32 v134, 0xbfb8aa3b, v134
	v_mul_f32_e32 v94, 0xbfb8aa3b, v94
	v_exp_f32_e32 v134, v134
	v_exp_f32_e32 v94, v94
	v_add_f32_e32 v135, v135, v143
	v_add_f32_e32 v95, v95, v145
	v_mul_f32_e32 v135, 0xbfb8aa3b, v135
	v_mul_f32_e32 v95, 0xbfb8aa3b, v95
	v_exp_f32_e32 v135, v135
	v_exp_f32_e32 v95, v95
	v_add_f32_e32 v136, v136, v143
	v_add_f32_e32 v96, v96, v145
	v_mul_f32_e32 v136, 0xbfb8aa3b, v136
	v_mul_f32_e32 v96, 0xbfb8aa3b, v96
	v_exp_f32_e32 v136, v136
	v_exp_f32_e32 v96, v96
	v_add_f32_e32 v137, v137, v143
	v_add_f32_e32 v97, v97, v145
	v_mul_f32_e32 v137, 0xbfb8aa3b, v137
	v_mul_f32_e32 v97, 0xbfb8aa3b, v97
	v_exp_f32_e32 v137, v137
	v_exp_f32_e32 v97, v97
	v_add_f32_e32 v126, v126, v144
	v_add_f32_e32 v90, v90, v154
	v_mul_f32_e32 v126, 0xbfb8aa3b, v126
	v_mul_f32_e32 v90, 0xbfb8aa3b, v90
	v_exp_f32_e32 v126, v126
	v_exp_f32_e32 v90, v90
	v_add_f32_e32 v127, v127, v144
	v_add_f32_e32 v91, v91, v154
	v_mul_f32_e32 v127, 0xbfb8aa3b, v127
	v_mul_f32_e32 v91, 0xbfb8aa3b, v91
	v_exp_f32_e32 v127, v127
	v_exp_f32_e32 v91, v91
	v_add_f32_e32 v128, v128, v144
	v_add_f32_e32 v92, v92, v154
	v_mul_f32_e32 v128, 0xbfb8aa3b, v128
	v_mul_f32_e32 v92, 0xbfb8aa3b, v92
	v_exp_f32_e32 v128, v128
	v_exp_f32_e32 v92, v92
	v_add_f32_e32 v129, v129, v144
	v_add_f32_e32 v93, v93, v154
	v_mul_f32_e32 v129, 0xbfb8aa3b, v129
	v_mul_f32_e32 v93, 0xbfb8aa3b, v93
	v_exp_f32_e32 v129, v129
	v_exp_f32_e32 v93, v93
	v_pk_add_f32 v[134:135], v[134:135], 1.0 op_sel_hi:[1,0]
	v_pk_add_f32 v[94:95], v[94:95], 1.0 op_sel_hi:[1,0]
	v_lshlrev_b32_e32 v156, 16, v190
	v_and_b32_e32 v157, 0xffff0000, v190
	v_rcp_f32_e32 v134, v134
; DI float sigm(float x) { return 1.f / (1.f + __expf(-x)); }
; DI u32x4 pack8(const float* f) { u32x4 o; o.x = pack2(f[0], f[1]); o.y = pack2(f[2], f[3]); o.z = pack2(f[4], f[5]); o.w = pack2(f[6], f[7]); return o; }
; DI int tid512() { int t = threadIdx.x; asm volatile("" : "+v"(t)); return t; }
; DI u32x4* merge_scratch(PREF p, int region) { const int t = tid512(); return (u32x4*)p.fbuf + (size_t)blockIdx.x * 40960 + region * 8192 + (t >> 6) * 1024 + (t & 63); }
; DI void gate_reg(PREF p, int l, int n, f32x4 (&acc)[2][2][4][2], int dt) {
;   const u32x4* sbn = merge_scratch(p, n);
;   u32x4* ssum = merge_scratch(p, 4);
;   const int t = tid512(), wid = t >> 6, lane = t & 63, wc = wid & 3, fr = lane & 15;
;   const float* bm = p.b_merge + (size_t)l * 4096 + n * 1024 + dt * 256 + wc * 32 + fr;
;   float bias[2][2];
; #pragma unroll
;   for (int bj = 0; bj < 2; ++bj)
; #pragma unroll
;     for (int nn = 0; nn < 2; ++nn) bias[bj][nn] = bm[bj * 128 + nn * 16];
; #pragma unroll
;   for (int ai = 0; ai < 2; ++ai)
; #pragma unroll
;     for (int bj = 0; bj < 2; ++bj) {
;       __builtin_amdgcn_sched_barrier(0);
;       u32x4 bn[4], pv[4];
; #pragma unroll
;       for (int m = 0; m < 4; ++m) {
;         bn[m] = sbn[((ai * 2 + bj) * 4 + m) * 64];
;         if (n > 0) pv[m] = ssum[((ai * 2 + bj) * 4 + m) * 64];
;       }
; #pragma unroll
;       for (int m = 0; m < 4; ++m) {
;         float b[8]; unpack8(bn[m], b);
;         float v[8];
; #pragma unroll
;         for (int nn = 0; nn < 2; ++nn)
; #pragma unroll
;           for (int j = 0; j < 4; ++j) v[nn * 4 + j] = sigm(acc[ai][bj][m][nn][j] + bias[bj][nn]) * b[nn * 4 + j];
;         if (n > 0) {
;           float o[8]; unpack8(pv[m], o);
; #pragma unroll
;           for (int e = 0; e < 8; ++e) v[e] += o[e];
;         }
;         if (n < 3) ssum[((ai * 2 + bj) * 4 + m) * 64] = pack8(v);
; #pragma unroll
;         for (int nn = 0; nn < 2; ++nn)
; #pragma unroll
;           for (int j = 0; j < 4; ++j) acc[ai][bj][m][nn][j] = v[nn * 4 + j];
;       }
;     }
; }
	v_rcp_f32_e32 v135, v135
	v_lshlrev_b32_e32 v164, 16, v206
	v_and_b32_e32 v165, 0xffff0000, v206
	v_rcp_f32_e32 v94, v94
	v_rcp_f32_e32 v95, v95
	v_pk_mul_f32 v[134:135], v[134:135], v[156:157]
	s_nop 0
	v_pk_fma_f32 v[134:135], v[94:95], v[164:165], v[134:135]
	v_lshlrev_b32_e32 v166, 16, v222
	v_and_b32_e32 v167, 0xffff0000, v222
	v_pk_add_f32 v[134:135], v[134:135], v[166:167]
	v_pk_add_f32 v[136:137], v[136:137], 1.0 op_sel_hi:[1,0]
	v_pk_add_f32 v[96:97], v[96:97], 1.0 op_sel_hi:[1,0]
	v_lshlrev_b32_e32 v156, 16, v191
	v_and_b32_e32 v157, 0xffff0000, v191
	v_rcp_f32_e32 v136, v136
	v_rcp_f32_e32 v137, v137
	v_lshlrev_b32_e32 v164, 16, v207
	v_and_b32_e32 v165, 0xffff0000, v207
	v_rcp_f32_e32 v96, v96
	v_rcp_f32_e32 v97, v97
	v_pk_mul_f32 v[136:137], v[136:137], v[156:157]
	s_nop 0
	v_pk_fma_f32 v[136:137], v[96:97], v[164:165], v[136:137]
	v_lshlrev_b32_e32 v166, 16, v223
	v_and_b32_e32 v167, 0xffff0000, v223
	v_pk_add_f32 v[136:137], v[136:137], v[166:167]
	v_pk_add_f32 v[126:127], v[126:127], 1.0 op_sel_hi:[1,0]
	v_pk_add_f32 v[90:91], v[90:91], 1.0 op_sel_hi:[1,0]
	v_lshlrev_b32_e32 v156, 16, v192
	v_and_b32_e32 v157, 0xffff0000, v192
	v_rcp_f32_e32 v126, v126
	v_rcp_f32_e32 v127, v127
	v_lshlrev_b32_e32 v164, 16, v208
	v_and_b32_e32 v165, 0xffff0000, v208
	v_rcp_f32_e32 v90, v90
	v_rcp_f32_e32 v91, v91
	v_pk_mul_f32 v[126:127], v[126:127], v[156:157]
	s_nop 0
	v_pk_fma_f32 v[126:127], v[90:91], v[164:165], v[126:127]
	v_lshlrev_b32_e32 v166, 16, v224
	v_and_b32_e32 v167, 0xffff0000, v224
	v_pk_add_f32 v[126:127], v[126:127], v[166:167]
	v_pk_add_f32 v[128:129], v[128:129], 1.0 op_sel_hi:[1,0]
	v_pk_add_f32 v[92:93], v[92:93], 1.0 op_sel_hi:[1,0]
	v_lshlrev_b32_e32 v156, 16, v193
	v_and_b32_e32 v157, 0xffff0000, v193
	v_rcp_f32_e32 v128, v128
	v_rcp_f32_e32 v129, v129
	v_lshlrev_b32_e32 v164, 16, v209
	v_and_b32_e32 v165, 0xffff0000, v209
	v_rcp_f32_e32 v92, v92
	v_rcp_f32_e32 v93, v93
	v_pk_mul_f32 v[128:129], v[128:129], v[156:157]
	s_nop 0
	v_pk_fma_f32 v[128:129], v[92:93], v[164:165], v[128:129]
	v_lshlrev_b32_e32 v166, 16, v225
	v_and_b32_e32 v167, 0xffff0000, v225
	v_pk_add_f32 v[128:129], v[128:129], v[166:167]
	s_waitcnt vmcnt(12)
	v_add_f32_e32 v122, v122, v143
	v_add_f32_e32 v86, v86, v145
	v_mul_f32_e32 v122, 0xbfb8aa3b, v122
	v_mul_f32_e32 v86, 0xbfb8aa3b, v86
	v_exp_f32_e32 v122, v122
	v_exp_f32_e32 v86, v86
	v_add_f32_e32 v123, v123, v143
	v_add_f32_e32 v87, v87, v145
	v_mul_f32_e32 v123, 0xbfb8aa3b, v123
	v_mul_f32_e32 v87, 0xbfb8aa3b, v87
	v_exp_f32_e32 v123, v123
	v_exp_f32_e32 v87, v87
	v_add_f32_e32 v124, v124, v143
	v_add_f32_e32 v88, v88, v145
	v_mul_f32_e32 v124, 0xbfb8aa3b, v124
	v_mul_f32_e32 v88, 0xbfb8aa3b, v88
	v_exp_f32_e32 v124, v124
	v_exp_f32_e32 v88, v88
	v_add_f32_e32 v125, v125, v143
	v_add_f32_e32 v89, v89, v145
	v_mul_f32_e32 v125, 0xbfb8aa3b, v125
	v_mul_f32_e32 v89, 0xbfb8aa3b, v89
	v_exp_f32_e32 v125, v125
	v_exp_f32_e32 v89, v89
	v_add_f32_e32 v114, v114, v144
	v_add_f32_e32 v82, v82, v154
	v_mul_f32_e32 v114, 0xbfb8aa3b, v114
	v_mul_f32_e32 v82, 0xbfb8aa3b, v82
	v_exp_f32_e32 v114, v114
	v_exp_f32_e32 v82, v82
	v_add_f32_e32 v115, v115, v144
	v_add_f32_e32 v83, v83, v154
	v_mul_f32_e32 v115, 0xbfb8aa3b, v115
	v_mul_f32_e32 v83, 0xbfb8aa3b, v83
	v_exp_f32_e32 v115, v115
	v_exp_f32_e32 v83, v83
	v_add_f32_e32 v116, v116, v144
	v_add_f32_e32 v84, v84, v154
	v_mul_f32_e32 v116, 0xbfb8aa3b, v116
	v_mul_f32_e32 v84, 0xbfb8aa3b, v84
	v_exp_f32_e32 v116, v116
	v_exp_f32_e32 v84, v84
	v_add_f32_e32 v117, v117, v144
	v_add_f32_e32 v85, v85, v154
	v_mul_f32_e32 v117, 0xbfb8aa3b, v117
	v_mul_f32_e32 v85, 0xbfb8aa3b, v85
	v_exp_f32_e32 v117, v117
	v_exp_f32_e32 v85, v85
	v_pk_add_f32 v[122:123], v[122:123], 1.0 op_sel_hi:[1,0]
	v_pk_add_f32 v[86:87], v[86:87], 1.0 op_sel_hi:[1,0]
	v_lshlrev_b32_e32 v156, 16, v194
	v_and_b32_e32 v157, 0xffff0000, v194
	v_rcp_f32_e32 v122, v122
	v_rcp_f32_e32 v123, v123
	v_lshlrev_b32_e32 v164, 16, v210
	v_and_b32_e32 v165, 0xffff0000, v210
	v_rcp_f32_e32 v86, v86
	v_rcp_f32_e32 v87, v87
	v_pk_mul_f32 v[122:123], v[122:123], v[156:157]
	s_nop 0
	v_pk_fma_f32 v[122:123], v[86:87], v[164:165], v[122:123]
	v_lshlrev_b32_e32 v166, 16, v226
	v_and_b32_e32 v167, 0xffff0000, v226
	v_pk_add_f32 v[122:123], v[122:123], v[166:167]
	v_pk_add_f32 v[124:125], v[124:125], 1.0 op_sel_hi:[1,0]
	v_pk_add_f32 v[88:89], v[88:89], 1.0 op_sel_hi:[1,0]
	v_lshlrev_b32_e32 v156, 16, v195
	v_and_b32_e32 v157, 0xffff0000, v195
	v_rcp_f32_e32 v124, v124
	v_rcp_f32_e32 v125, v125
	v_lshlrev_b32_e32 v164, 16, v211
	v_and_b32_e32 v165, 0xffff0000, v211
	v_rcp_f32_e32 v88, v88
	v_rcp_f32_e32 v89, v89
	v_pk_mul_f32 v[124:125], v[124:125], v[156:157]
	s_nop 0
	v_pk_fma_f32 v[124:125], v[88:89], v[164:165], v[124:125]
	v_lshlrev_b32_e32 v166, 16, v227
	v_and_b32_e32 v167, 0xffff0000, v227
	v_pk_add_f32 v[124:125], v[124:125], v[166:167]
	v_pk_add_f32 v[114:115], v[114:115], 1.0 op_sel_hi:[1,0]
	v_pk_add_f32 v[82:83], v[82:83], 1.0 op_sel_hi:[1,0]
	v_lshlrev_b32_e32 v156, 16, v196
	v_and_b32_e32 v157, 0xffff0000, v196
	v_rcp_f32_e32 v114, v114
	v_rcp_f32_e32 v115, v115
	v_lshlrev_b32_e32 v164, 16, v212
	v_and_b32_e32 v165, 0xffff0000, v212
	v_rcp_f32_e32 v82, v82
	v_rcp_f32_e32 v83, v83
	v_pk_mul_f32 v[114:115], v[114:115], v[156:157]
	s_nop 0
	v_pk_fma_f32 v[114:115], v[82:83], v[164:165], v[114:115]
	v_lshlrev_b32_e32 v166, 16, v228
	v_and_b32_e32 v167, 0xffff0000, v228
	v_pk_add_f32 v[114:115], v[114:115], v[166:167]
	v_pk_add_f32 v[116:117], v[116:117], 1.0 op_sel_hi:[1,0]
	v_pk_add_f32 v[84:85], v[84:85], 1.0 op_sel_hi:[1,0]
	v_lshlrev_b32_e32 v156, 16, v197
	v_and_b32_e32 v157, 0xffff0000, v197
	v_rcp_f32_e32 v116, v116
	v_rcp_f32_e32 v117, v117
	v_lshlrev_b32_e32 v164, 16, v213
	v_and_b32_e32 v165, 0xffff0000, v213
	v_rcp_f32_e32 v84, v84
	v_rcp_f32_e32 v85, v85
	v_pk_mul_f32 v[116:117], v[116:117], v[156:157]
	s_nop 0
	v_pk_fma_f32 v[116:117], v[84:85], v[164:165], v[116:117]
	v_lshlrev_b32_e32 v166, 16, v229
	v_and_b32_e32 v167, 0xffff0000, v229
	v_pk_add_f32 v[116:117], v[116:117], v[166:167]
	s_waitcnt vmcnt(9)
; DI float sigm(float x) { return 1.f / (1.f + __expf(-x)); }
; DI u32x4 pack8(const float* f) { u32x4 o; o.x = pack2(f[0], f[1]); o.y = pack2(f[2], f[3]); o.z = pack2(f[4], f[5]); o.w = pack2(f[6], f[7]); return o; }
; DI int tid512() { int t = threadIdx.x; asm volatile("" : "+v"(t)); return t; }
; DI u32x4* merge_scratch(PREF p, int region) { const int t = tid512(); return (u32x4*)p.fbuf + (size_t)blockIdx.x * 40960 + region * 8192 + (t >> 6) * 1024 + (t & 63); }
; DI void gate_reg(PREF p, int l, int n, f32x4 (&acc)[2][2][4][2], int dt) {
;   const u32x4* sbn = merge_scratch(p, n);
;   u32x4* ssum = merge_scratch(p, 4);
;   const int t = tid512(), wid = t >> 6, lane = t & 63, wc = wid & 3, fr = lane & 15;
;   const float* bm = p.b_merge + (size_t)l * 4096 + n * 1024 + dt * 256 + wc * 32 + fr;
;   float bias[2][2];
; #pragma unroll
;   for (int bj = 0; bj < 2; ++bj)
; #pragma unroll
;     for (int nn = 0; nn < 2; ++nn) bias[bj][nn] = bm[bj * 128 + nn * 16];
; #pragma unroll
;   for (int ai = 0; ai < 2; ++ai)
; #pragma unroll
;     for (int bj = 0; bj < 2; ++bj) {
;       __builtin_amdgcn_sched_barrier(0);
;       u32x4 bn[4], pv[4];
; #pragma unroll
;       for (int m = 0; m < 4; ++m) {
;         bn[m] = sbn[((ai * 2 + bj) * 4 + m) * 64];
;         if (n > 0) pv[m] = ssum[((ai * 2 + bj) * 4 + m) * 64];
;       }
; #pragma unroll
;       for (int m = 0; m < 4; ++m) {
;         float b[8]; unpack8(bn[m], b);
;         float v[8];
; #pragma unroll
;         for (int nn = 0; nn < 2; ++nn)
; #pragma unroll
;           for (int j = 0; j < 4; ++j) v[nn * 4 + j] = sigm(acc[ai][bj][m][nn][j] + bias[bj][nn]) * b[nn * 4 + j];
;         if (n > 0) {
;           float o[8]; unpack8(pv[m], o);
; #pragma unroll
;           for (int e = 0; e < 8; ++e) v[e] += o[e];
;         }
;         if (n < 3) ssum[((ai * 2 + bj) * 4 + m) * 64] = pack8(v);
; #pragma unroll
;         for (int nn = 0; nn < 2; ++nn)
; #pragma unroll
;           for (int j = 0; j < 4; ++j) acc[ai][bj][m][nn][j] = v[nn * 4 + j];
;       }
;     }
; }
	v_add_f32_e32 v78, v78, v143
	v_add_f32_e32 v46, v46, v145
	v_mul_f32_e32 v78, 0xbfb8aa3b, v78
	v_mul_f32_e32 v46, 0xbfb8aa3b, v46
	v_exp_f32_e32 v78, v78
	v_exp_f32_e32 v46, v46
	v_add_f32_e32 v79, v79, v143
	v_add_f32_e32 v47, v47, v145
	v_mul_f32_e32 v79, 0xbfb8aa3b, v79
	v_mul_f32_e32 v47, 0xbfb8aa3b, v47
	v_exp_f32_e32 v79, v79
	v_exp_f32_e32 v47, v47
	v_add_f32_e32 v80, v80, v143
	v_add_f32_e32 v48, v48, v145
	v_mul_f32_e32 v80, 0xbfb8aa3b, v80
	v_mul_f32_e32 v48, 0xbfb8aa3b, v48
	v_exp_f32_e32 v80, v80
	v_exp_f32_e32 v48, v48
	v_add_f32_e32 v81, v81, v143
	v_add_f32_e32 v49, v49, v145
	v_mul_f32_e32 v81, 0xbfb8aa3b, v81
	v_mul_f32_e32 v49, 0xbfb8aa3b, v49
	v_exp_f32_e32 v81, v81
	v_exp_f32_e32 v49, v49
	v_add_f32_e32 v74, v74, v144
	v_add_f32_e32 v38, v38, v154
	v_mul_f32_e32 v74, 0xbfb8aa3b, v74
	v_mul_f32_e32 v38, 0xbfb8aa3b, v38
	v_exp_f32_e32 v74, v74
	v_exp_f32_e32 v38, v38
	v_add_f32_e32 v75, v75, v144
	v_add_f32_e32 v39, v39, v154
	v_mul_f32_e32 v75, 0xbfb8aa3b, v75
	v_mul_f32_e32 v39, 0xbfb8aa3b, v39
	v_exp_f32_e32 v75, v75
	v_exp_f32_e32 v39, v39
	v_add_f32_e32 v76, v76, v144
	v_add_f32_e32 v40, v40, v154
	v_mul_f32_e32 v76, 0xbfb8aa3b, v76
	v_mul_f32_e32 v40, 0xbfb8aa3b, v40
	v_exp_f32_e32 v76, v76
	v_exp_f32_e32 v40, v40
	v_add_f32_e32 v77, v77, v144
	v_add_f32_e32 v41, v41, v154
	v_mul_f32_e32 v77, 0xbfb8aa3b, v77
	v_mul_f32_e32 v41, 0xbfb8aa3b, v41
	v_exp_f32_e32 v77, v77
	v_exp_f32_e32 v41, v41
	v_pk_add_f32 v[78:79], v[78:79], 1.0 op_sel_hi:[1,0]
	v_pk_add_f32 v[46:47], v[46:47], 1.0 op_sel_hi:[1,0]
	v_lshlrev_b32_e32 v156, 16, v230
	v_and_b32_e32 v157, 0xffff0000, v230
	v_rcp_f32_e32 v78, v78
	v_rcp_f32_e32 v79, v79
	v_lshlrev_b32_e32 v164, 16, v246
	v_and_b32_e32 v165, 0xffff0000, v246
	v_rcp_f32_e32 v46, v46
	v_rcp_f32_e32 v47, v47
	v_pk_mul_f32 v[78:79], v[78:79], v[156:157]
	s_nop 0
	v_pk_fma_f32 v[78:79], v[46:47], v[164:165], v[78:79]
	v_lshlrev_b32_e32 v166, 16, v30
	v_and_b32_e32 v167, 0xffff0000, v30
	v_pk_add_f32 v[78:79], v[78:79], v[166:167]
	v_pk_add_f32 v[80:81], v[80:81], 1.0 op_sel_hi:[1,0]
	v_pk_add_f32 v[48:49], v[48:49], 1.0 op_sel_hi:[1,0]
	v_lshlrev_b32_e32 v156, 16, v231
	v_and_b32_e32 v157, 0xffff0000, v231
	v_rcp_f32_e32 v80, v80
	v_rcp_f32_e32 v81, v81
	v_lshlrev_b32_e32 v164, 16, v247
	v_and_b32_e32 v165, 0xffff0000, v247
	v_rcp_f32_e32 v48, v48
	v_rcp_f32_e32 v49, v49
	v_pk_mul_f32 v[80:81], v[80:81], v[156:157]
	s_nop 0
	v_pk_fma_f32 v[80:81], v[48:49], v[164:165], v[80:81]
	v_lshlrev_b32_e32 v166, 16, v31
	v_and_b32_e32 v167, 0xffff0000, v31
	v_pk_add_f32 v[80:81], v[80:81], v[166:167]
	v_pk_add_f32 v[74:75], v[74:75], 1.0 op_sel_hi:[1,0]
	v_pk_add_f32 v[38:39], v[38:39], 1.0 op_sel_hi:[1,0]
	v_lshlrev_b32_e32 v156, 16, v232
	v_and_b32_e32 v157, 0xffff0000, v232
	v_rcp_f32_e32 v74, v74
	v_rcp_f32_e32 v75, v75
	v_lshlrev_b32_e32 v164, 16, v248
	v_and_b32_e32 v165, 0xffff0000, v248
	v_rcp_f32_e32 v38, v38
	v_rcp_f32_e32 v39, v39
	v_pk_mul_f32 v[74:75], v[74:75], v[156:157]
	s_nop 0
	v_pk_fma_f32 v[74:75], v[38:39], v[164:165], v[74:75]
	v_lshlrev_b32_e32 v166, 16, v32
	v_and_b32_e32 v167, 0xffff0000, v32
	v_pk_add_f32 v[74:75], v[74:75], v[166:167]
	v_pk_add_f32 v[76:77], v[76:77], 1.0 op_sel_hi:[1,0]
	v_pk_add_f32 v[40:41], v[40:41], 1.0 op_sel_hi:[1,0]
	v_lshlrev_b32_e32 v156, 16, v233
	v_and_b32_e32 v157, 0xffff0000, v233
	v_rcp_f32_e32 v76, v76
	v_rcp_f32_e32 v77, v77
	v_lshlrev_b32_e32 v164, 16, v249
	v_and_b32_e32 v165, 0xffff0000, v249
	v_rcp_f32_e32 v40, v40
	v_rcp_f32_e32 v41, v41
	v_pk_mul_f32 v[76:77], v[76:77], v[156:157]
	s_nop 0
	v_pk_fma_f32 v[76:77], v[40:41], v[164:165], v[76:77]
	v_lshlrev_b32_e32 v166, 16, v33
	v_and_b32_e32 v167, 0xffff0000, v33
	v_pk_add_f32 v[76:77], v[76:77], v[166:167]
	s_waitcnt vmcnt(6)
	v_add_f32_e32 v70, v70, v143
	v_add_f32_e32 v34, v34, v145
	v_mul_f32_e32 v70, 0xbfb8aa3b, v70
	v_mul_f32_e32 v34, 0xbfb8aa3b, v34
	v_exp_f32_e32 v70, v70
	v_exp_f32_e32 v34, v34
	v_add_f32_e32 v71, v71, v143
	v_add_f32_e32 v35, v35, v145
	v_mul_f32_e32 v71, 0xbfb8aa3b, v71
	v_mul_f32_e32 v35, 0xbfb8aa3b, v35
	v_exp_f32_e32 v71, v71
	v_exp_f32_e32 v35, v35
	v_add_f32_e32 v72, v72, v143
	v_add_f32_e32 v36, v36, v145
	v_mul_f32_e32 v72, 0xbfb8aa3b, v72
	v_mul_f32_e32 v36, 0xbfb8aa3b, v36
	v_exp_f32_e32 v72, v72
	v_exp_f32_e32 v36, v36
	v_add_f32_e32 v73, v73, v143
	v_add_f32_e32 v37, v37, v145
	v_mul_f32_e32 v73, 0xbfb8aa3b, v73
	v_mul_f32_e32 v37, 0xbfb8aa3b, v37
	v_exp_f32_e32 v73, v73
	v_exp_f32_e32 v37, v37
	v_add_f32_e32 v66, v66, v144
	v_add_f32_e32 v26, v26, v154
	v_mul_f32_e32 v66, 0xbfb8aa3b, v66
	v_mul_f32_e32 v26, 0xbfb8aa3b, v26
	v_exp_f32_e32 v66, v66
	v_exp_f32_e32 v26, v26
	v_add_f32_e32 v67, v67, v144
	v_add_f32_e32 v27, v27, v154
	v_mul_f32_e32 v67, 0xbfb8aa3b, v67
	v_mul_f32_e32 v27, 0xbfb8aa3b, v27
	v_exp_f32_e32 v67, v67
	v_exp_f32_e32 v27, v27
	v_add_f32_e32 v68, v68, v144
	v_add_f32_e32 v28, v28, v154
	v_mul_f32_e32 v68, 0xbfb8aa3b, v68
	v_mul_f32_e32 v28, 0xbfb8aa3b, v28
	v_exp_f32_e32 v68, v68
	v_exp_f32_e32 v28, v28
	v_add_f32_e32 v69, v69, v144
	v_add_f32_e32 v29, v29, v154
	v_mul_f32_e32 v69, 0xbfb8aa3b, v69
	v_mul_f32_e32 v29, 0xbfb8aa3b, v29
	v_exp_f32_e32 v69, v69
	v_exp_f32_e32 v29, v29
	v_pk_add_f32 v[70:71], v[70:71], 1.0 op_sel_hi:[1,0]
	v_pk_add_f32 v[34:35], v[34:35], 1.0 op_sel_hi:[1,0]
	v_lshlrev_b32_e32 v156, 16, v234
	v_and_b32_e32 v157, 0xffff0000, v234
	v_rcp_f32_e32 v70, v70
	v_rcp_f32_e32 v71, v71
	v_lshlrev_b32_e32 v164, 16, v250
	v_and_b32_e32 v165, 0xffff0000, v250
	v_rcp_f32_e32 v34, v34
	v_rcp_f32_e32 v35, v35
	v_pk_mul_f32 v[70:71], v[70:71], v[156:157]
	s_nop 0
	v_pk_fma_f32 v[70:71], v[34:35], v[164:165], v[70:71]
; DI float sigm(float x) { return 1.f / (1.f + __expf(-x)); }
; DI u32x4 pack8(const float* f) { u32x4 o; o.x = pack2(f[0], f[1]); o.y = pack2(f[2], f[3]); o.z = pack2(f[4], f[5]); o.w = pack2(f[6], f[7]); return o; }
; DI int tid512() { int t = threadIdx.x; asm volatile("" : "+v"(t)); return t; }
; DI u32x4* merge_scratch(PREF p, int region) { const int t = tid512(); return (u32x4*)p.fbuf + (size_t)blockIdx.x * 40960 + region * 8192 + (t >> 6) * 1024 + (t & 63); }
; DI void gate_reg(PREF p, int l, int n, f32x4 (&acc)[2][2][4][2], int dt) {
;   const u32x4* sbn = merge_scratch(p, n);
;   u32x4* ssum = merge_scratch(p, 4);
;   const int t = tid512(), wid = t >> 6, lane = t & 63, wc = wid & 3, fr = lane & 15;
;   const float* bm = p.b_merge + (size_t)l * 4096 + n * 1024 + dt * 256 + wc * 32 + fr;
;   float bias[2][2];
; #pragma unroll
;   for (int bj = 0; bj < 2; ++bj)
; #pragma unroll
;     for (int nn = 0; nn < 2; ++nn) bias[bj][nn] = bm[bj * 128 + nn * 16];
; #pragma unroll
;   for (int ai = 0; ai < 2; ++ai)
; #pragma unroll
;     for (int bj = 0; bj < 2; ++bj) {
;       __builtin_amdgcn_sched_barrier(0);
;       u32x4 bn[4], pv[4];
; #pragma unroll
;       for (int m = 0; m < 4; ++m) {
;         bn[m] = sbn[((ai * 2 + bj) * 4 + m) * 64];
;         if (n > 0) pv[m] = ssum[((ai * 2 + bj) * 4 + m) * 64];
;       }
; #pragma unroll
;       for (int m = 0; m < 4; ++m) {
;         float b[8]; unpack8(bn[m], b);
;         float v[8];
; #pragma unroll
;         for (int nn = 0; nn < 2; ++nn)
; #pragma unroll
;           for (int j = 0; j < 4; ++j) v[nn * 4 + j] = sigm(acc[ai][bj][m][nn][j] + bias[bj][nn]) * b[nn * 4 + j];
;         if (n > 0) {
;           float o[8]; unpack8(pv[m], o);
; #pragma unroll
;           for (int e = 0; e < 8; ++e) v[e] += o[e];
;         }
;         if (n < 3) ssum[((ai * 2 + bj) * 4 + m) * 64] = pack8(v);
; #pragma unroll
;         for (int nn = 0; nn < 2; ++nn)
; #pragma unroll
;           for (int j = 0; j < 4; ++j) acc[ai][bj][m][nn][j] = v[nn * 4 + j];
;       }
;     }
; }
	v_lshlrev_b32_e32 v166, 16, v42
	v_and_b32_e32 v167, 0xffff0000, v42
	v_pk_add_f32 v[70:71], v[70:71], v[166:167]
	v_pk_add_f32 v[72:73], v[72:73], 1.0 op_sel_hi:[1,0]
	v_pk_add_f32 v[36:37], v[36:37], 1.0 op_sel_hi:[1,0]
	v_lshlrev_b32_e32 v156, 16, v235
	v_and_b32_e32 v157, 0xffff0000, v235
	v_rcp_f32_e32 v72, v72
	v_rcp_f32_e32 v73, v73
	v_lshlrev_b32_e32 v164, 16, v251
	v_and_b32_e32 v165, 0xffff0000, v251
	v_rcp_f32_e32 v36, v36
	v_rcp_f32_e32 v37, v37
	v_pk_mul_f32 v[72:73], v[72:73], v[156:157]
	s_nop 0
	v_pk_fma_f32 v[72:73], v[36:37], v[164:165], v[72:73]
	v_lshlrev_b32_e32 v166, 16, v43
	v_and_b32_e32 v167, 0xffff0000, v43
	v_pk_add_f32 v[72:73], v[72:73], v[166:167]
	v_pk_add_f32 v[66:67], v[66:67], 1.0 op_sel_hi:[1,0]
	v_pk_add_f32 v[26:27], v[26:27], 1.0 op_sel_hi:[1,0]
	v_lshlrev_b32_e32 v156, 16, v236
	v_and_b32_e32 v157, 0xffff0000, v236
	v_rcp_f32_e32 v66, v66
	v_rcp_f32_e32 v67, v67
	v_lshlrev_b32_e32 v164, 16, v252
	v_and_b32_e32 v165, 0xffff0000, v252
	v_rcp_f32_e32 v26, v26
	v_rcp_f32_e32 v27, v27
	v_pk_mul_f32 v[66:67], v[66:67], v[156:157]
	s_nop 0
	v_pk_fma_f32 v[66:67], v[26:27], v[164:165], v[66:67]
	v_lshlrev_b32_e32 v166, 16, v44
	v_and_b32_e32 v167, 0xffff0000, v44
	v_pk_add_f32 v[66:67], v[66:67], v[166:167]
	v_pk_add_f32 v[68:69], v[68:69], 1.0 op_sel_hi:[1,0]
	v_pk_add_f32 v[28:29], v[28:29], 1.0 op_sel_hi:[1,0]
	v_lshlrev_b32_e32 v156, 16, v237
	v_and_b32_e32 v157, 0xffff0000, v237
	v_rcp_f32_e32 v68, v68
	v_rcp_f32_e32 v69, v69
	v_lshlrev_b32_e32 v164, 16, v253
	v_and_b32_e32 v165, 0xffff0000, v253
	v_rcp_f32_e32 v28, v28
	v_rcp_f32_e32 v29, v29
	v_pk_mul_f32 v[68:69], v[68:69], v[156:157]
	s_nop 0
	v_pk_fma_f32 v[68:69], v[28:29], v[164:165], v[68:69]
	v_lshlrev_b32_e32 v166, 16, v45
	v_and_b32_e32 v167, 0xffff0000, v45
	v_pk_add_f32 v[68:69], v[68:69], v[166:167]
	s_waitcnt vmcnt(3)
	v_add_f32_e32 v62, v62, v143
	v_add_f32_e32 v22, v22, v145
	v_mul_f32_e32 v62, 0xbfb8aa3b, v62
	v_mul_f32_e32 v22, 0xbfb8aa3b, v22
	v_exp_f32_e32 v62, v62
	v_exp_f32_e32 v22, v22
	v_add_f32_e32 v63, v63, v143
	v_add_f32_e32 v23, v23, v145
	v_mul_f32_e32 v63, 0xbfb8aa3b, v63
	v_mul_f32_e32 v23, 0xbfb8aa3b, v23
	v_exp_f32_e32 v63, v63
	v_exp_f32_e32 v23, v23
	v_add_f32_e32 v64, v64, v143
	v_add_f32_e32 v24, v24, v145
	v_mul_f32_e32 v64, 0xbfb8aa3b, v64
	v_mul_f32_e32 v24, 0xbfb8aa3b, v24
	v_exp_f32_e32 v64, v64
	v_exp_f32_e32 v24, v24
	v_add_f32_e32 v65, v65, v143
	v_add_f32_e32 v25, v25, v145
	v_mul_f32_e32 v65, 0xbfb8aa3b, v65
	v_mul_f32_e32 v25, 0xbfb8aa3b, v25
	v_exp_f32_e32 v65, v65
	v_exp_f32_e32 v25, v25
	v_add_f32_e32 v58, v58, v144
	v_add_f32_e32 v14, v14, v154
	v_mul_f32_e32 v58, 0xbfb8aa3b, v58
	v_mul_f32_e32 v14, 0xbfb8aa3b, v14
	v_exp_f32_e32 v58, v58
	v_exp_f32_e32 v14, v14
	v_add_f32_e32 v59, v59, v144
	v_add_f32_e32 v15, v15, v154
	v_mul_f32_e32 v59, 0xbfb8aa3b, v59
	v_mul_f32_e32 v15, 0xbfb8aa3b, v15
	v_exp_f32_e32 v59, v59
	v_exp_f32_e32 v15, v15
	v_add_f32_e32 v60, v60, v144
	v_add_f32_e32 v16, v16, v154
	v_mul_f32_e32 v60, 0xbfb8aa3b, v60
	v_mul_f32_e32 v16, 0xbfb8aa3b, v16
	v_exp_f32_e32 v60, v60
	v_exp_f32_e32 v16, v16
	v_add_f32_e32 v61, v61, v144
	v_add_f32_e32 v17, v17, v154
	v_mul_f32_e32 v61, 0xbfb8aa3b, v61
	v_mul_f32_e32 v17, 0xbfb8aa3b, v17
	v_exp_f32_e32 v61, v61
	v_exp_f32_e32 v17, v17
	v_pk_add_f32 v[62:63], v[62:63], 1.0 op_sel_hi:[1,0]
	v_pk_add_f32 v[22:23], v[22:23], 1.0 op_sel_hi:[1,0]
	v_lshlrev_b32_e32 v156, 16, v238
	v_and_b32_e32 v157, 0xffff0000, v238
	v_rcp_f32_e32 v62, v62
	v_rcp_f32_e32 v63, v63
	v_lshlrev_b32_e32 v164, 16, v6
	v_and_b32_e32 v165, 0xffff0000, v6
	v_rcp_f32_e32 v22, v22
	v_rcp_f32_e32 v23, v23
	v_pk_mul_f32 v[62:63], v[62:63], v[156:157]
	s_nop 0
	v_pk_fma_f32 v[62:63], v[22:23], v[164:165], v[62:63]
	v_lshlrev_b32_e32 v166, 16, v118
	v_and_b32_e32 v167, 0xffff0000, v118
	v_pk_add_f32 v[62:63], v[62:63], v[166:167]
	v_pk_add_f32 v[64:65], v[64:65], 1.0 op_sel_hi:[1,0]
	v_pk_add_f32 v[24:25], v[24:25], 1.0 op_sel_hi:[1,0]
	v_lshlrev_b32_e32 v156, 16, v239
	v_and_b32_e32 v157, 0xffff0000, v239
	v_rcp_f32_e32 v64, v64
	v_rcp_f32_e32 v65, v65
	v_lshlrev_b32_e32 v164, 16, v7
	v_and_b32_e32 v165, 0xffff0000, v7
	v_rcp_f32_e32 v24, v24
	v_rcp_f32_e32 v25, v25
	v_pk_mul_f32 v[64:65], v[64:65], v[156:157]
	s_nop 0
	v_pk_fma_f32 v[64:65], v[24:25], v[164:165], v[64:65]
	v_lshlrev_b32_e32 v166, 16, v119
	v_and_b32_e32 v167, 0xffff0000, v119
	v_pk_add_f32 v[64:65], v[64:65], v[166:167]
	v_pk_add_f32 v[58:59], v[58:59], 1.0 op_sel_hi:[1,0]
	v_pk_add_f32 v[14:15], v[14:15], 1.0 op_sel_hi:[1,0]
	v_lshlrev_b32_e32 v156, 16, v240
	v_and_b32_e32 v157, 0xffff0000, v240
	v_rcp_f32_e32 v58, v58
	v_rcp_f32_e32 v59, v59
	v_lshlrev_b32_e32 v164, 16, v8
	v_and_b32_e32 v165, 0xffff0000, v8
	v_rcp_f32_e32 v14, v14
	v_rcp_f32_e32 v15, v15
	v_pk_mul_f32 v[58:59], v[58:59], v[156:157]
	s_nop 0
	v_pk_fma_f32 v[58:59], v[14:15], v[164:165], v[58:59]
	v_lshlrev_b32_e32 v166, 16, v120
	v_and_b32_e32 v167, 0xffff0000, v120
	v_pk_add_f32 v[58:59], v[58:59], v[166:167]
	v_pk_add_f32 v[60:61], v[60:61], 1.0 op_sel_hi:[1,0]
	v_pk_add_f32 v[16:17], v[16:17], 1.0 op_sel_hi:[1,0]
	v_lshlrev_b32_e32 v156, 16, v241
	v_and_b32_e32 v157, 0xffff0000, v241
	v_rcp_f32_e32 v60, v60
	v_rcp_f32_e32 v61, v61
	v_lshlrev_b32_e32 v164, 16, v9
	v_and_b32_e32 v165, 0xffff0000, v9
	v_rcp_f32_e32 v16, v16
	v_rcp_f32_e32 v17, v17
	v_pk_mul_f32 v[60:61], v[60:61], v[156:157]
	s_nop 0
	v_pk_fma_f32 v[60:61], v[16:17], v[164:165], v[60:61]
	v_lshlrev_b32_e32 v166, 16, v121
	v_and_b32_e32 v167, 0xffff0000, v121
	v_pk_add_f32 v[60:61], v[60:61], v[166:167]
	s_waitcnt vmcnt(0)
; DI float sigm(float x) { return 1.f / (1.f + __expf(-x)); }
; DI u32x4 pack8(const float* f) { u32x4 o; o.x = pack2(f[0], f[1]); o.y = pack2(f[2], f[3]); o.z = pack2(f[4], f[5]); o.w = pack2(f[6], f[7]); return o; }
; DI void lds_barrier() { asm volatile("s_waitcnt lgkmcnt(0)\n\ts_barrier" ::: "memory"); }
; template <int AI, int BJ>
; DI void stage_q(const f32x4 (&acc)[2][2][4][2], float* Cs) {
;   const int t = tid512(), wid = t >> 6, lane = t & 63, wr = wid >> 2, wc = wid & 3, fr = lane & 15, fq = lane >> 4;
;   lds_barrier();
; #pragma unroll
;   for (int m = 0; m < 4; ++m)
; #pragma unroll
;     for (int n = 0; n < 2; ++n)
; #pragma unroll
;       for (int j = 0; j < 4; ++j) Cs[(wr * 64 + m * 16 + fq * 4 + j) * CST + wc * 32 + n * 16 + fr] = acc[AI][BJ][m][n][j];
;   lds_barrier();
; DI void gate_reg(PREF p, int l, int n, f32x4 (&acc)[2][2][4][2], int dt) {
;   const u32x4* sbn = merge_scratch(p, n);
;   u32x4* ssum = merge_scratch(p, 4);
;   const int t = tid512(), wid = t >> 6, lane = t & 63, wc = wid & 3, fr = lane & 15;
;   const float* bm = p.b_merge + (size_t)l * 4096 + n * 1024 + dt * 256 + wc * 32 + fr;
;   float bias[2][2];
; #pragma unroll
;   for (int bj = 0; bj < 2; ++bj)
; #pragma unroll
;     for (int nn = 0; nn < 2; ++nn) bias[bj][nn] = bm[bj * 128 + nn * 16];
; #pragma unroll
;   for (int ai = 0; ai < 2; ++ai)
; #pragma unroll
;     for (int bj = 0; bj < 2; ++bj) {
;       __builtin_amdgcn_sched_barrier(0);
;       u32x4 bn[4], pv[4];
; #pragma unroll
;       for (int m = 0; m < 4; ++m) {
;         bn[m] = sbn[((ai * 2 + bj) * 4 + m) * 64];
;         if (n > 0) pv[m] = ssum[((ai * 2 + bj) * 4 + m) * 64];
;       }
; #pragma unroll
;       for (int m = 0; m < 4; ++m) {
;         float b[8]; unpack8(bn[m], b);
;         float v[8];
; #pragma unroll
;         for (int nn = 0; nn < 2; ++nn)
; #pragma unroll
;           for (int j = 0; j < 4; ++j) v[nn * 4 + j] = sigm(acc[ai][bj][m][nn][j] + bias[bj][nn]) * b[nn * 4 + j];
;         if (n > 0) {
;           float o[8]; unpack8(pv[m], o);
; #pragma unroll
;           for (int e = 0; e < 8; ++e) v[e] += o[e];
;         }
;         if (n < 3) ssum[((ai * 2 + bj) * 4 + m) * 64] = pack8(v);
; #pragma unroll
;         for (int nn = 0; nn < 2; ++nn)
; #pragma unroll
;           for (int j = 0; j < 4; ++j) acc[ai][bj][m][nn][j] = v[nn * 4 + j];
;       }
;     }
; }
	v_add_f32_e32 v54, v54, v143
	v_add_f32_e32 v10, v10, v145
	v_mul_f32_e32 v54, 0xbfb8aa3b, v54
	v_mul_f32_e32 v10, 0xbfb8aa3b, v10
	v_exp_f32_e32 v54, v54
	v_exp_f32_e32 v10, v10
	v_add_f32_e32 v55, v55, v143
	v_add_f32_e32 v11, v11, v145
	v_mul_f32_e32 v55, 0xbfb8aa3b, v55
	v_mul_f32_e32 v11, 0xbfb8aa3b, v11
	v_exp_f32_e32 v55, v55
	v_exp_f32_e32 v11, v11
	v_add_f32_e32 v56, v56, v143
	v_add_f32_e32 v12, v12, v145
	v_mul_f32_e32 v56, 0xbfb8aa3b, v56
	v_mul_f32_e32 v12, 0xbfb8aa3b, v12
	v_exp_f32_e32 v56, v56
	v_exp_f32_e32 v12, v12
	v_add_f32_e32 v57, v57, v143
	v_add_f32_e32 v13, v13, v145
	v_mul_f32_e32 v57, 0xbfb8aa3b, v57
	v_mul_f32_e32 v13, 0xbfb8aa3b, v13
	v_exp_f32_e32 v57, v57
	v_exp_f32_e32 v13, v13
	v_add_f32_e32 v50, v50, v144
	v_add_f32_e32 v2, v2, v154
	v_mul_f32_e32 v50, 0xbfb8aa3b, v50
	v_mul_f32_e32 v2, 0xbfb8aa3b, v2
	v_exp_f32_e32 v50, v50
	v_exp_f32_e32 v2, v2
	v_add_f32_e32 v51, v51, v144
	v_add_f32_e32 v3, v3, v154
	v_mul_f32_e32 v51, 0xbfb8aa3b, v51
	v_mul_f32_e32 v3, 0xbfb8aa3b, v3
	v_exp_f32_e32 v51, v51
	v_exp_f32_e32 v3, v3
	v_add_f32_e32 v52, v52, v144
	v_add_f32_e32 v4, v4, v154
	v_mul_f32_e32 v52, 0xbfb8aa3b, v52
	v_mul_f32_e32 v4, 0xbfb8aa3b, v4
	v_exp_f32_e32 v52, v52
	v_exp_f32_e32 v4, v4
	v_add_f32_e32 v53, v53, v144
	v_add_f32_e32 v5, v5, v154
	v_mul_f32_e32 v53, 0xbfb8aa3b, v53
	v_mul_f32_e32 v5, 0xbfb8aa3b, v5
	v_exp_f32_e32 v53, v53
	v_exp_f32_e32 v5, v5
	v_pk_add_f32 v[54:55], v[54:55], 1.0 op_sel_hi:[1,0]
	v_pk_add_f32 v[10:11], v[10:11], 1.0 op_sel_hi:[1,0]
	v_lshlrev_b32_e32 v156, 16, v242
	v_and_b32_e32 v157, 0xffff0000, v242
	v_rcp_f32_e32 v54, v54
	v_rcp_f32_e32 v55, v55
	v_lshlrev_b32_e32 v164, 16, v18
	v_and_b32_e32 v165, 0xffff0000, v18
	v_rcp_f32_e32 v10, v10
	v_rcp_f32_e32 v11, v11
	v_pk_mul_f32 v[54:55], v[54:55], v[156:157]
	s_nop 0
	v_pk_fma_f32 v[54:55], v[10:11], v[164:165], v[54:55]
	v_lshlrev_b32_e32 v166, 16, v130
	v_and_b32_e32 v167, 0xffff0000, v130
	v_pk_add_f32 v[54:55], v[54:55], v[166:167]
	v_pk_add_f32 v[56:57], v[56:57], 1.0 op_sel_hi:[1,0]
	v_pk_add_f32 v[12:13], v[12:13], 1.0 op_sel_hi:[1,0]
	v_lshlrev_b32_e32 v156, 16, v243
	v_and_b32_e32 v157, 0xffff0000, v243
	v_rcp_f32_e32 v56, v56
	v_rcp_f32_e32 v57, v57
	v_lshlrev_b32_e32 v164, 16, v19
	v_and_b32_e32 v165, 0xffff0000, v19
	v_rcp_f32_e32 v12, v12
	v_rcp_f32_e32 v13, v13
	v_pk_mul_f32 v[56:57], v[56:57], v[156:157]
	s_nop 0
	v_pk_fma_f32 v[56:57], v[12:13], v[164:165], v[56:57]
	v_lshlrev_b32_e32 v166, 16, v131
	v_and_b32_e32 v167, 0xffff0000, v131
	v_pk_add_f32 v[56:57], v[56:57], v[166:167]
	v_pk_add_f32 v[50:51], v[50:51], 1.0 op_sel_hi:[1,0]
	v_pk_add_f32 v[2:3], v[2:3], 1.0 op_sel_hi:[1,0]
	v_lshlrev_b32_e32 v156, 16, v244
	v_and_b32_e32 v157, 0xffff0000, v244
	v_rcp_f32_e32 v50, v50
	v_rcp_f32_e32 v51, v51
	v_lshlrev_b32_e32 v164, 16, v20
	v_and_b32_e32 v165, 0xffff0000, v20
	v_rcp_f32_e32 v2, v2
	v_rcp_f32_e32 v3, v3
	v_pk_mul_f32 v[50:51], v[50:51], v[156:157]
	s_nop 0
	v_pk_fma_f32 v[50:51], v[2:3], v[164:165], v[50:51]
	v_lshlrev_b32_e32 v166, 16, v132
	v_and_b32_e32 v167, 0xffff0000, v132
	v_pk_add_f32 v[50:51], v[50:51], v[166:167]
	v_pk_add_f32 v[52:53], v[52:53], 1.0 op_sel_hi:[1,0]
	v_pk_add_f32 v[4:5], v[4:5], 1.0 op_sel_hi:[1,0]
	v_lshlrev_b32_e32 v156, 16, v245
	v_and_b32_e32 v157, 0xffff0000, v245
	v_rcp_f32_e32 v52, v52
	v_rcp_f32_e32 v53, v53
	v_lshlrev_b32_e32 v164, 16, v21
	v_and_b32_e32 v165, 0xffff0000, v21
	v_rcp_f32_e32 v4, v4
	v_rcp_f32_e32 v5, v5
	v_pk_mul_f32 v[52:53], v[52:53], v[156:157]
	s_nop 0
	v_pk_fma_f32 v[52:53], v[4:5], v[164:165], v[52:53]
	v_lshlrev_b32_e32 v166, 16, v133
	v_and_b32_e32 v167, 0xffff0000, v133
	v_pk_add_f32 v[52:53], v[52:53], v[166:167]
	v_lshrrev_b32_e32 v156, 8, v168
	v_lshlrev_b32_e32 v156, 6, v156
	v_bfe_u32 v157, v168, 4, 2
	v_lshl_add_u32 v156, v157, 2, v156
	v_mul_u32_u24_e32 v156, 0x84, v156
	v_bfe_u32 v157, v168, 6, 2
	v_lshlrev_b32_e32 v157, 5, v157
	v_and_b32_e32 v164, 15, v168
	v_add3_u32 v156, v156, v157, v164
	v_lshlrev_b32_e32 v156, 2, v156
	v_lshrrev_b32_e32 v157, 4, v168
	v_lshlrev_b32_e32 v165, 11, v157
	v_mul_u32_u24_e32 v157, 0x84, v157
	v_lshl_add_u32 v157, v164, 3, v157
	v_lshlrev_b32_e32 v157, 2, v157
	v_lshl_add_u32 v165, v164, 4, v165
	v_mov_b32_e32 v164, v165
	s_waitcnt lgkmcnt(0)
	s_barrier
; DI u32x4 pack8(const float* f) { u32x4 o; o.x = pack2(f[0], f[1]); o.y = pack2(f[2], f[3]); o.z = pack2(f[4], f[5]); o.w = pack2(f[6], f[7]); return o; }
; DI void lds_barrier() { asm volatile("s_waitcnt lgkmcnt(0)\n\ts_barrier" ::: "memory"); }
; DI int tid512() { int t = threadIdx.x; asm volatile("" : "+v"(t)); return t; }
; template <int AI, int BJ>
; DI void stage_q(const f32x4 (&acc)[2][2][4][2], float* Cs) {
;   const int t = tid512(), wid = t >> 6, lane = t & 63, wr = wid >> 2, wc = wid & 3, fr = lane & 15, fq = lane >> 4;
;   lds_barrier();
; #pragma unroll
;   for (int m = 0; m < 4; ++m)
; #pragma unroll
;     for (int n = 0; n < 2; ++n)
; #pragma unroll
;       for (int j = 0; j < 4; ++j) Cs[(wr * 64 + m * 16 + fq * 4 + j) * CST + wc * 32 + n * 16 + fr] = acc[AI][BJ][m][n][j];
;   lds_barrier();
; }
; template <int AI, int BJ>
; DI void mg_quadrant(PREF p, const f32x4 (&acc)[2][2][4][2], int mt, int dt, float* Cs) {
;   const int t = tid512();
;   const int row0 = mt * 256 + AI * 128, col0 = dt * 256 + BJ * 128;
;   stage_q<AI, BJ>(acc, Cs);
; #pragma unroll
;   for (int q = 0; q < 4; ++q) {
;     int r = (t >> 4) + 32 * q, c = (t & 15) * 8;
;     float v[8]; ld8(Cs + r * CST + c, v);
;     *(u32x4*)(p.mg + (size_t)(row0 + r) * 1024 + col0 + c) = pack8(v);
;   }
; }
	ds_write_b32 v156, v158 offset:0
	ds_write_b32 v156, v159 offset:528
	ds_write_b32 v156, v160 offset:1056
	ds_write_b32 v156, v161 offset:1584
	ds_write_b32 v156, v150 offset:64
	ds_write_b32 v156, v151 offset:592
	ds_write_b32 v156, v152 offset:1120
	ds_write_b32 v156, v153 offset:1648
	ds_write_b32 v156, v146 offset:8448
	ds_write_b32 v156, v147 offset:8976
	ds_write_b32 v156, v148 offset:9504
	ds_write_b32 v156, v149 offset:10032
	ds_write_b32 v156, v138 offset:8512
	ds_write_b32 v156, v139 offset:9040
	ds_write_b32 v156, v140 offset:9568
	ds_write_b32 v156, v141 offset:10096
	ds_write_b32 v156, v134 offset:16896
	ds_write_b32 v156, v135 offset:17424
	ds_write_b32 v156, v136 offset:17952
	ds_write_b32 v156, v137 offset:18480
	ds_write_b32 v156, v126 offset:16960
	ds_write_b32 v156, v127 offset:17488
	ds_write_b32 v156, v128 offset:18016
	ds_write_b32 v156, v129 offset:18544
	ds_write_b32 v156, v122 offset:25344
	ds_write_b32 v156, v123 offset:25872
	ds_write_b32 v156, v124 offset:26400
	ds_write_b32 v156, v125 offset:26928
	ds_write_b32 v156, v114 offset:25408
	ds_write_b32 v156, v115 offset:25936
	ds_write_b32 v156, v116 offset:26464
	ds_write_b32 v156, v117 offset:26992
	s_waitcnt lgkmcnt(0)
	s_barrier
	s_add_i32 s0, s12, 0
	s_lshl_b32 s0, s0, 11
	s_lshl_b32 s1, s43, 8
	s_add_u32 s0, s0, s1
	s_add_u32 s0, s36, s0
	s_addc_u32 s1, s37, 0
	ds_read_b128 v[182:185], v157 offset:0
	ds_read_b128 v[186:189], v157 offset:16
	ds_read_b128 v[190:193], v157 offset:16896
	ds_read_b128 v[194:197], v157 offset:16912
	ds_read_b128 v[198:201], v157 offset:33792
	ds_read_b128 v[202:205], v157 offset:33808
	ds_read_b128 v[206:209], v157 offset:50688
	ds_read_b128 v[210:213], v157 offset:50704
	s_waitcnt lgkmcnt(6)
	v_cvt_pk_bf16_f32 v182, v182, v183
	v_cvt_pk_bf16_f32 v183, v184, v185
	v_cvt_pk_bf16_f32 v184, v186, v187
	v_cvt_pk_bf16_f32 v185, v188, v189
	global_store_dwordx4 v164, v[182:185], s[0:1]
	s_waitcnt lgkmcnt(4)
	v_cvt_pk_bf16_f32 v190, v190, v191
	v_cvt_pk_bf16_f32 v191, v192, v193
	v_cvt_pk_bf16_f32 v192, v194, v195
	v_cvt_pk_bf16_f32 v193, v196, v197
	v_add_u32_e32 v164, 0x10000, v164
	global_store_dwordx4 v164, v[190:193], s[0:1]
	s_waitcnt lgkmcnt(2)
	v_cvt_pk_bf16_f32 v198, v198, v199
	v_cvt_pk_bf16_f32 v199, v200, v201
	v_cvt_pk_bf16_f32 v200, v202, v203
	v_cvt_pk_bf16_f32 v201, v204, v205
	v_add_u32_e32 v164, 0x10000, v164
	global_store_dwordx4 v164, v[198:201], s[0:1]
	s_waitcnt lgkmcnt(0)
	v_cvt_pk_bf16_f32 v206, v206, v207
	v_cvt_pk_bf16_f32 v207, v208, v209
	v_cvt_pk_bf16_f32 v208, v210, v211
	v_cvt_pk_bf16_f32 v209, v212, v213
	v_add_u32_e32 v164, 0x10000, v164
	global_store_dwordx4 v164, v[206:209], s[0:1]
	v_mov_b32_e32 v164, v165
	s_waitcnt lgkmcnt(0)
	s_barrier
	ds_write_b32 v156, v78 offset:0
	ds_write_b32 v156, v79 offset:528
	ds_write_b32 v156, v80 offset:1056
	ds_write_b32 v156, v81 offset:1584
	ds_write_b32 v156, v74 offset:64
	ds_write_b32 v156, v75 offset:592
	ds_write_b32 v156, v76 offset:1120
	ds_write_b32 v156, v77 offset:1648
	ds_write_b32 v156, v70 offset:8448
	ds_write_b32 v156, v71 offset:8976
	ds_write_b32 v156, v72 offset:9504
	ds_write_b32 v156, v73 offset:10032
	ds_write_b32 v156, v66 offset:8512
	ds_write_b32 v156, v67 offset:9040
	ds_write_b32 v156, v68 offset:9568
	ds_write_b32 v156, v69 offset:10096
	ds_write_b32 v156, v62 offset:16896
	ds_write_b32 v156, v63 offset:17424
	ds_write_b32 v156, v64 offset:17952
	ds_write_b32 v156, v65 offset:18480
	ds_write_b32 v156, v58 offset:16960
	ds_write_b32 v156, v59 offset:17488
	ds_write_b32 v156, v60 offset:18016
	ds_write_b32 v156, v61 offset:18544
	ds_write_b32 v156, v54 offset:25344
	ds_write_b32 v156, v55 offset:25872
	ds_write_b32 v156, v56 offset:26400
	ds_write_b32 v156, v57 offset:26928
	ds_write_b32 v156, v50 offset:25408
	ds_write_b32 v156, v51 offset:25936
	ds_write_b32 v156, v52 offset:26464
	ds_write_b32 v156, v53 offset:26992
	s_waitcnt lgkmcnt(0)
	s_barrier
	s_add_i32 s0, s12, 128
	s_lshl_b32 s0, s0, 11
	s_lshl_b32 s1, s43, 8
	s_add_u32 s0, s0, s1
	s_add_u32 s0, s36, s0
	s_addc_u32 s1, s37, 0
	ds_read_b128 v[182:185], v157 offset:0
	ds_read_b128 v[186:189], v157 offset:16
	ds_read_b128 v[190:193], v157 offset:16896
	ds_read_b128 v[194:197], v157 offset:16912
	ds_read_b128 v[198:201], v157 offset:33792
	ds_read_b128 v[202:205], v157 offset:33808
	ds_read_b128 v[206:209], v157 offset:50688
	ds_read_b128 v[210:213], v157 offset:50704
	s_waitcnt lgkmcnt(6)
	v_cvt_pk_bf16_f32 v182, v182, v183
	v_cvt_pk_bf16_f32 v183, v184, v185
	v_cvt_pk_bf16_f32 v184, v186, v187
	v_cvt_pk_bf16_f32 v185, v188, v189
	global_store_dwordx4 v164, v[182:185], s[0:1]
	s_waitcnt lgkmcnt(4)
	v_cvt_pk_bf16_f32 v190, v190, v191
	v_cvt_pk_bf16_f32 v191, v192, v193
	v_cvt_pk_bf16_f32 v192, v194, v195
	v_cvt_pk_bf16_f32 v193, v196, v197
	v_add_u32_e32 v164, 0x10000, v164
	global_store_dwordx4 v164, v[190:193], s[0:1]
	s_waitcnt lgkmcnt(2)
	v_cvt_pk_bf16_f32 v198, v198, v199
	v_cvt_pk_bf16_f32 v199, v200, v201
	v_cvt_pk_bf16_f32 v200, v202, v203
	v_cvt_pk_bf16_f32 v201, v204, v205
	v_add_u32_e32 v164, 0x10000, v164
	global_store_dwordx4 v164, v[198:201], s[0:1]
	s_waitcnt lgkmcnt(0)
	v_cvt_pk_bf16_f32 v206, v206, v207
	v_cvt_pk_bf16_f32 v207, v208, v209
	v_cvt_pk_bf16_f32 v208, v210, v211
	v_cvt_pk_bf16_f32 v209, v212, v213
	v_add_u32_e32 v164, 0x10000, v164
	global_store_dwordx4 v164, v[206:209], s[0:1]
	s_branch .LBB0_101
